# UP epilogue: row scale of the value branch folded into the sigmoid denominator (one multiply less per output)
# speedup vs baseline: 1.0053x; 1.0053x over previous
;     __device__ __forceinline__ void operator()(const Acc& acc, const Unit& u, int wr, int wc, int fr, int fq, LAS unsigned char* lds, f32x4 epar) const {
;     ...
;         LAS float* pw = (LAS float*)(lds + STAGE_BYTES + 64 + (wr * 4 + wc) * 1024);
;         *(LAS f32x4*)(pw + (fq * 16 + fr) * 4) = epar;
;         asm volatile("s_waitcnt lgkmcnt(0)" ::: "memory");
;         float w0[NV], w1[NV], w2[NV], bb[NV];
; #pragma unroll
;         for (int i = 0; i < NV; i += 4) { const f32x4 a = *(const LAS f32x4*)(pw + NV * fq + i), b = *(const LAS f32x4*)(pw + 32 + NV * fq + i), c = *(const LAS f32x4*)(pw + 64 + NV * fq + i);
;             f32x4 d = (f32x4){0.f, 0.f, 0.f, 0.f}; if (MODE == 0) d = *(const LAS f32x4*)(pw + 96 + NV * fq + i);
; #pragma unroll
;             for (int j = 0; j < 4; ++j) { w0[i + j] = a[j]; w1[i + j] = b[j]; w2[i + j] = c[j]; bb[i + j] = d[j]; } }
;         float sq[2][4];
; #pragma unroll
;         for (int ai = 0; ai < 2; ++ai)
; #pragma unroll
;             for (int m = 0; m < 4; ++m) sq[ai][m] = pw[128 + ai * 64 + m * 16 + fr];
; #pragma unroll
;         for (int ai = 0; ai < 2; ++ai) {
;             const int strip = u.pm * 4 + ai * 2 + wr;
;             float p1prev[NV], p2prev[NV];
; #pragma unroll
;             for (int i = 0; i < NV; ++i) { p1prev[i] = 0.f; p2prev[i] = 0.f; }
; #pragma unroll
;             for (int m = 0; m < 4; ++m) {
;                 const int r = u.pm * BM + ai * HALF + wr * 64 + m * 16 + fr;
;                 const float rs = __builtin_amdgcn_rsqf(sq[ai][m] * (1.0f / DM) + RMS_EPS);
;                 float X[NV], Y[NV], o[NV];
;                 if (MODE == 0) {
; #pragma unroll
;                     for (int n = 0; n < 2; ++n)
; #pragma unroll
;                         for (int j = 0; j < 4; ++j) { X[n * 4 + j] = acc[ai][0][m][n][j] * rs; Y[n * 4 + j] = acc[ai][1][m][n][j] * rs; }
;                 } else {
; #pragma unroll
;                     for (int j = 0; j < 4; ++j) { X[j] = (acc[ai][0][m][1][j] * rs) * (acc[ai][1][m][0][j] * rs); Y[j] = acc[ai][0][m][0][j] * rs; }
;                 }
; #pragma unroll
;                 for (int i = 0; i < NV; ++i) {
;                     const float a1 = dpp_rot<0x121>(X[i]), a2 = dpp_rot<0x122>(X[i]);
;                     const float q1 = fr >= 1 ? a1 : p1prev[i], q2 = fr >= 2 ? a2 : p2prev[i];
;                     p1prev[i] = a1; p2prev[i] = a2;
.LBB0_692:
	ds_write_b128 v198, v[72:75]
	s_mov_b64 s[24:25], exec
	s_waitcnt lgkmcnt(0)
	ds_read_b128 v[88:91], v199
	ds_read_b128 v[92:95], v199 offset:16
	ds_read_b128 v[128:131], v199 offset:128
	ds_read_b128 v[132:135], v199 offset:144
	ds_read_b128 v[136:139], v199 offset:256
	ds_read_b128 v[140:143], v199 offset:272
	ds_read_b128 v[174:177], v199 offset:384
	ds_read_b128 v[178:181], v199 offset:400
	ds_read2_b32 v[182:183], v191 offset0:128 offset1:144
	ds_read2_b32 v[184:185], v191 offset0:160 offset1:176
	ds_read2_b32 v[76:77], v191 offset0:192 offset1:208
	ds_read2_b32 v[78:79], v191 offset0:224 offset1:240
	v_lshl_add_u32 v230, s70, 8, v190
	v_lshl_or_b32 v231, s72, 7, v192
	v_mul_u32_u24_e32 v230, 0x1600, v230
	s_lshl_b32 s26, s70, 2
	s_add_i32 s26, s26, s14
	s_mul_i32 s16, s26, 6
	v_and_b32_e32 v233, 15, v190
	v_lshl_add_u32 v230, v231, 1, v230
	v_add_u32_e32 v233, s16, v233
	v_mul_u32_u24_e32 v233, 0x1600, v233
	s_nop 0
	v_lshl_add_u32 v233, v231, 1, v233
	s_waitcnt lgkmcnt(0)
	v_mul_f32_e32 v88, 0xbfb8aa3b, v88
	v_mul_f32_e32 v89, 0xbfb8aa3b, v89
	v_mul_f32_e32 v90, 0xbfb8aa3b, v90
	v_mul_f32_e32 v91, 0xbfb8aa3b, v91
	v_mul_f32_e32 v92, 0xbfb8aa3b, v92
	v_mul_f32_e32 v93, 0xbfb8aa3b, v93
	v_mul_f32_e32 v94, 0xbfb8aa3b, v94
	v_mul_f32_e32 v95, 0xbfb8aa3b, v95
	v_mul_f32_e32 v128, 0xbfb8aa3b, v128
	v_mul_f32_e32 v129, 0xbfb8aa3b, v129
	v_mul_f32_e32 v130, 0xbfb8aa3b, v130
	v_mul_f32_e32 v131, 0xbfb8aa3b, v131
	v_mul_f32_e32 v132, 0xbfb8aa3b, v132
	v_mul_f32_e32 v133, 0xbfb8aa3b, v133
	v_mul_f32_e32 v134, 0xbfb8aa3b, v134
	v_mul_f32_e32 v135, 0xbfb8aa3b, v135
	v_mul_f32_e32 v136, 0xbfb8aa3b, v136
	v_mul_f32_e32 v137, 0xbfb8aa3b, v137
	v_mul_f32_e32 v138, 0xbfb8aa3b, v138
	v_mul_f32_e32 v139, 0xbfb8aa3b, v139
	v_mul_f32_e32 v140, 0xbfb8aa3b, v140
	v_mul_f32_e32 v141, 0xbfb8aa3b, v141
	v_mul_f32_e32 v142, 0xbfb8aa3b, v142
	v_mul_f32_e32 v143, 0xbfb8aa3b, v143
	v_mul_f32_e32 v174, 0xbfb8aa3b, v174
	v_mul_f32_e32 v175, 0xbfb8aa3b, v175
	v_mul_f32_e32 v176, 0xbfb8aa3b, v176
	v_mul_f32_e32 v177, 0xbfb8aa3b, v177
	v_mul_f32_e32 v178, 0xbfb8aa3b, v178
	v_mul_f32_e32 v179, 0xbfb8aa3b, v179
	v_mul_f32_e32 v180, 0xbfb8aa3b, v180
	v_mul_f32_e32 v181, 0xbfb8aa3b, v181
	v_fmamk_f32 v182, v182, 0x3a800000, v200
	v_fmamk_f32 v183, v183, 0x3a800000, v200
	v_fmamk_f32 v184, v184, 0x3a800000, v200
	v_fmamk_f32 v185, v185, 0x3a800000, v200
	v_fmamk_f32 v76, v76, 0x3a800000, v200
	v_fmamk_f32 v77, v77, 0x3a800000, v200
	v_fmamk_f32 v78, v78, 0x3a800000, v200
	v_fmamk_f32 v79, v79, 0x3a800000, v200
	v_mul_f32_e32 v202, 0xbfb8aa3b, v182
	v_mul_f32_e32 v203, 0xbfb8aa3b, v183
	v_mul_f32_e32 v204, 0xbfb8aa3b, v184
	v_mul_f32_e32 v205, 0xbfb8aa3b, v185
	v_mul_f32_e32 v206, 0xbfb8aa3b, v76
	v_mul_f32_e32 v207, 0xbfb8aa3b, v77
	v_mul_f32_e32 v208, 0xbfb8aa3b, v78
	v_mul_f32_e32 v209, 0xbfb8aa3b, v79
	v_rsq_f32_e32 v182, v182
	v_rsq_f32_e32 v183, v183
	v_rsq_f32_e32 v184, v184
	v_rsq_f32_e32 v185, v185
	v_rsq_f32_e32 v76, v76
	v_rsq_f32_e32 v77, v77
	v_rsq_f32_e32 v78, v78
	v_rsq_f32_e32 v79, v79
	s_nop 0
	v_mul_f32_e32 v202, v202, v182
	v_mul_f32_e32 v203, v203, v183
	v_mul_f32_e32 v204, v204, v184
	v_mul_f32_e32 v205, v205, v185
	v_mul_f32_e32 v206, v206, v76
	v_mul_f32_e32 v207, v207, v77
	v_mul_f32_e32 v208, v208, v78
	v_mul_f32_e32 v209, v209, v79
	v_mul_f32_e32 v152, v152, v182
	v_mul_f32_e32 v153, v153, v182
	v_mul_f32_e32 v154, v154, v182
	v_mul_f32_e32 v155, v155, v182
	v_mul_f32_e32 v144, v144, v182
	v_mul_f32_e32 v145, v145, v182
	v_mul_f32_e32 v146, v146, v182
	v_mul_f32_e32 v147, v147, v182
	v_fma_f32 v210, v152, v136, v174
	v_fma_f32 v211, v153, v137, v175
	v_fma_f32 v212, v154, v138, v176
	v_fma_f32 v213, v155, v139, v177
	v_fma_f32 v214, v144, v140, v178
	v_fma_f32 v215, v145, v141, v179
	v_fma_f32 v216, v146, v142, v180
	v_fma_f32 v217, v147, v143, v181
	v_mul_f32_e32 v218, v156, v182
	v_mul_f32_e32 v219, v157, v182
	v_mul_f32_e32 v220, v158, v182
	v_mul_f32_e32 v221, v159, v182
	v_mul_f32_e32 v222, v148, v182
	v_mul_f32_e32 v223, v149, v182
	v_mul_f32_e32 v224, v150, v182
	v_mul_f32_e32 v225, v151, v182
	v_cvt_pk_bf16_f32 v236, v152, v153
	v_cvt_pk_bf16_f32 v237, v154, v155
	v_cvt_pk_bf16_f32 v238, v144, v145
	v_cvt_pk_bf16_f32 v239, v146, v147
	v_cvt_pk_bf16_f32 v240, v218, v219
	v_cvt_pk_bf16_f32 v241, v220, v221
	v_cvt_pk_bf16_f32 v242, v222, v223
	v_cvt_pk_bf16_f32 v243, v224, v225
	v_add_u32_e32 v234, 0x2c00, v233
	v_add_u32_e32 v235, 0x5800, v233
	s_andn2_b64 exec, exec, s[8:9]
	global_store_dwordx4 v234, v[236:239], s[42:43]
	global_store_dwordx4 v235, v[240:243], s[42:43]
	s_mov_b64 exec, s[24:25]
	v_fmac_f32_dpp v210, v152, v128 row_shr:1 row_mask:0xf bank_mask:0xf
	v_fmac_f32_dpp v211, v153, v129 row_shr:1 row_mask:0xf bank_mask:0xf
	v_fmac_f32_dpp v212, v154, v130 row_shr:1 row_mask:0xf bank_mask:0xf
	v_fmac_f32_dpp v213, v155, v131 row_shr:1 row_mask:0xf bank_mask:0xf
	v_fmac_f32_dpp v214, v144, v132 row_shr:1 row_mask:0xf bank_mask:0xf
	v_fmac_f32_dpp v215, v145, v133 row_shr:1 row_mask:0xf bank_mask:0xf
	v_fmac_f32_dpp v216, v146, v134 row_shr:1 row_mask:0xf bank_mask:0xf
	v_fmac_f32_dpp v217, v147, v135 row_shr:1 row_mask:0xf bank_mask:0xf
	v_fmac_f32_dpp v210, v152, v88 row_shr:2 row_mask:0xf bank_mask:0xf
	v_fmac_f32_dpp v211, v153, v89 row_shr:2 row_mask:0xf bank_mask:0xf
	v_fmac_f32_dpp v212, v154, v90 row_shr:2 row_mask:0xf bank_mask:0xf
	v_fmac_f32_dpp v213, v155, v91 row_shr:2 row_mask:0xf bank_mask:0xf
	v_fmac_f32_dpp v214, v144, v92 row_shr:2 row_mask:0xf bank_mask:0xf
	v_fmac_f32_dpp v215, v145, v93 row_shr:2 row_mask:0xf bank_mask:0xf
	v_fmac_f32_dpp v216, v146, v94 row_shr:2 row_mask:0xf bank_mask:0xf
; __device__ __forceinline__ unsigned cvt_pk_bf16(float lo, float hi) { unsigned r; asm volatile("v_cvt_pk_bf16_f32 %0, %1, %2" : "=v"(r) : "v"(lo), "v"(hi)); return r; }
; __device__ __forceinline__ float silu_f(float x) { return x * __builtin_amdgcn_rcpf(1.0f + __builtin_amdgcn_exp2f(x * -1.44269504f)); }
; template <int CTRL> __device__ __forceinline__ float dpp_rot(float x) { return __int_as_float(__builtin_amdgcn_mov_dpp(__float_as_int(x), CTRL, 0xf, 0xf, false)); }
;     __device__ __forceinline__ void operator()(const Acc& acc, const Unit& u, int wr, int wc, int fr, int fq, LAS unsigned char* lds, f32x4 epar) const {
;     ...
; #pragma unroll
;                 for (int i = 0; i < NV; ++i) {
;                     const float a1 = dpp_rot<0x121>(X[i]), a2 = dpp_rot<0x122>(X[i]);
;                     const float q1 = fr >= 1 ? a1 : p1prev[i], q2 = fr >= 2 ? a2 : p2prev[i];
;                     p1prev[i] = a1; p2prev[i] = a2;
;                     const float cv = w2[i] * X[i] + w1[i] * q1 + w0[i] * q2 + bb[i];
;                     o[i] = MODE == 0 ? silu_f(cv) * Y[i] : cv * Y[i];
;                 }
;                 if (m == 0 && fr < 2) {
;                     bf16_t* hx = halo + ((size_t)strip * 6 + 2 + fr) * C + c0; bf16_t* hy = halo + ((size_t)strip * 6 + 4 + fr) * C + c0;
;                     u32x4 px, py; px.x = cvt_pk_bf16(X[0], X[1]); px.y = cvt_pk_bf16(X[2], X[3]); px.z = cvt_pk_bf16(X[4 % NV], X[5 % NV]); px.w = cvt_pk_bf16(X[6 % NV], X[7 % NV]);
;                     py.x = cvt_pk_bf16(Y[0], Y[1]); py.y = cvt_pk_bf16(Y[2], Y[3]); py.z = cvt_pk_bf16(Y[4 % NV], Y[5 % NV]); py.w = cvt_pk_bf16(Y[6 % NV], Y[7 % NV]);
;                     if (MODE == 0) { *(u32x4*)hx = px; *(u32x4*)hy = py; } else { u32x2 a; a.x = px.x; a.y = px.y; *(u32x2*)hx = a; u32x2 b; b.x = py.x; b.y = py.y; *(u32x2*)hy = b; }
;                 } else {
;                     if (MODE == 0) { u32x4 w; w.x = cvt_pk_bf16(o[0], o[1]); w.y = cvt_pk_bf16(o[2], o[3]); w.z = cvt_pk_bf16(o[4 % NV], o[5 % NV]); w.w = cvt_pk_bf16(o[6 % NV], o[7 % NV]);
;                         __builtin_nontemporal_store(w, (u32x4*)(out + (size_t)r * C + c0)); }
	v_fmac_f32_dpp v217, v147, v95 row_shr:2 row_mask:0xf bank_mask:0xf
	v_exp_f32_e32 v218, v210
	v_exp_f32_e32 v219, v211
	v_exp_f32_e32 v220, v212
	v_exp_f32_e32 v221, v213
	v_exp_f32_e32 v222, v214
	v_exp_f32_e32 v223, v215
	v_exp_f32_e32 v224, v216
	v_exp_f32_e32 v225, v217
	v_fma_f32 v218, v218, v202, v202
	v_fma_f32 v219, v219, v202, v202
	v_fma_f32 v220, v220, v202, v202
	v_fma_f32 v221, v221, v202, v202
	v_fma_f32 v222, v222, v202, v202
	v_fma_f32 v223, v223, v202, v202
	v_fma_f32 v224, v224, v202, v202
	v_fma_f32 v225, v225, v202, v202
	v_rcp_f32_e32 v218, v218
	v_rcp_f32_e32 v219, v219
	v_rcp_f32_e32 v220, v220
	v_rcp_f32_e32 v221, v221
	v_rcp_f32_e32 v222, v222
	v_rcp_f32_e32 v223, v223
	v_rcp_f32_e32 v224, v224
	v_rcp_f32_e32 v225, v225
	v_mul_f32_e32 v210, v210, v218
	v_mul_f32_e32 v211, v211, v219
	v_mul_f32_e32 v212, v212, v220
	v_mul_f32_e32 v213, v213, v221
	v_mul_f32_e32 v214, v214, v222
	v_mul_f32_e32 v215, v215, v223
	v_mul_f32_e32 v216, v216, v224
	v_mul_f32_e32 v217, v217, v225
	v_mul_f32_e32 v156, v210, v156
	v_mul_f32_e32 v157, v211, v157
	v_mul_f32_e32 v158, v212, v158
	v_mul_f32_e32 v159, v213, v159
	v_mul_f32_e32 v148, v214, v148
	v_mul_f32_e32 v149, v215, v149
	v_mul_f32_e32 v150, v216, v150
	v_mul_f32_e32 v151, v217, v151
	v_cvt_pk_bf16_f32 v226, v156, v157
	v_cvt_pk_bf16_f32 v227, v158, v159
	v_cvt_pk_bf16_f32 v228, v148, v149
	v_cvt_pk_bf16_f32 v229, v150, v151
	v_add_u32_e32 v234, 0x0, v230
	s_and_b64 exec, exec, s[8:9]
	global_store_dwordx4 v234, v[226:229], s[96:97] nt
	s_mov_b64 exec, s[24:25]
	v_mul_f32_e32 v124, v124, v183
	v_mul_f32_e32 v125, v125, v183
	v_mul_f32_e32 v126, v126, v183
	v_mul_f32_e32 v127, v127, v183
	v_mul_f32_e32 v120, v120, v183
	v_mul_f32_e32 v121, v121, v183
	v_mul_f32_e32 v122, v122, v183
	v_mul_f32_e32 v123, v123, v183
	v_fma_f32 v210, v124, v136, v174
	v_fma_f32 v211, v125, v137, v175
	v_fma_f32 v212, v126, v138, v176
	v_fma_f32 v213, v127, v139, v177
	v_fma_f32 v214, v120, v140, v178
	v_fma_f32 v215, v121, v141, v179
	v_fma_f32 v216, v122, v142, v180
	v_fma_f32 v217, v123, v143, v181
	v_fmac_f32_dpp v210, v124, v128 row_shr:1 row_mask:0xf bank_mask:0xf
	v_fmac_f32_dpp v211, v125, v129 row_shr:1 row_mask:0xf bank_mask:0xf
	v_fmac_f32_dpp v212, v126, v130 row_shr:1 row_mask:0xf bank_mask:0xf
	v_fmac_f32_dpp v213, v127, v131 row_shr:1 row_mask:0xf bank_mask:0xf
	v_fmac_f32_dpp v214, v120, v132 row_shr:1 row_mask:0xf bank_mask:0xf
	v_fmac_f32_dpp v215, v121, v133 row_shr:1 row_mask:0xf bank_mask:0xf
	v_fmac_f32_dpp v216, v122, v134 row_shr:1 row_mask:0xf bank_mask:0xf
	v_fmac_f32_dpp v217, v123, v135 row_shr:1 row_mask:0xf bank_mask:0xf
	v_fmac_f32_dpp v210, v124, v88 row_shr:2 row_mask:0xf bank_mask:0xf
	v_fmac_f32_dpp v211, v125, v89 row_shr:2 row_mask:0xf bank_mask:0xf
	v_fmac_f32_dpp v212, v126, v90 row_shr:2 row_mask:0xf bank_mask:0xf
	v_fmac_f32_dpp v213, v127, v91 row_shr:2 row_mask:0xf bank_mask:0xf
	v_fmac_f32_dpp v214, v120, v92 row_shr:2 row_mask:0xf bank_mask:0xf
	v_fmac_f32_dpp v215, v121, v93 row_shr:2 row_mask:0xf bank_mask:0xf
	v_fmac_f32_dpp v216, v122, v94 row_shr:2 row_mask:0xf bank_mask:0xf
	v_fmac_f32_dpp v217, v123, v95 row_shr:2 row_mask:0xf bank_mask:0xf
	v_fmac_f32_dpp v210, v152, v128 row_shl:15 row_mask:0xf bank_mask:0xf
	v_fmac_f32_dpp v211, v153, v129 row_shl:15 row_mask:0xf bank_mask:0xf
	v_fmac_f32_dpp v212, v154, v130 row_shl:15 row_mask:0xf bank_mask:0xf
	v_fmac_f32_dpp v213, v155, v131 row_shl:15 row_mask:0xf bank_mask:0xf
	v_fmac_f32_dpp v214, v144, v132 row_shl:15 row_mask:0xf bank_mask:0xf
	v_fmac_f32_dpp v215, v145, v133 row_shl:15 row_mask:0xf bank_mask:0xf
	v_fmac_f32_dpp v216, v146, v134 row_shl:15 row_mask:0xf bank_mask:0xf
	v_fmac_f32_dpp v217, v147, v135 row_shl:15 row_mask:0xf bank_mask:0xf
	v_fmac_f32_dpp v210, v152, v88 row_shl:14 row_mask:0xf bank_mask:0xf
	v_fmac_f32_dpp v211, v153, v89 row_shl:14 row_mask:0xf bank_mask:0xf
	v_fmac_f32_dpp v212, v154, v90 row_shl:14 row_mask:0xf bank_mask:0xf
	v_fmac_f32_dpp v213, v155, v91 row_shl:14 row_mask:0xf bank_mask:0xf
	v_fmac_f32_dpp v214, v144, v92 row_shl:14 row_mask:0xf bank_mask:0xf
	v_fmac_f32_dpp v215, v145, v93 row_shl:14 row_mask:0xf bank_mask:0xf
	v_fmac_f32_dpp v216, v146, v94 row_shl:14 row_mask:0xf bank_mask:0xf
	v_fmac_f32_dpp v217, v147, v95 row_shl:14 row_mask:0xf bank_mask:0xf
	v_exp_f32_e32 v218, v210
	v_exp_f32_e32 v219, v211
	v_exp_f32_e32 v220, v212
	v_exp_f32_e32 v221, v213
	v_exp_f32_e32 v222, v214
	v_exp_f32_e32 v223, v215
	v_exp_f32_e32 v224, v216
	v_exp_f32_e32 v225, v217
	v_fma_f32 v218, v218, v203, v203
	v_fma_f32 v219, v219, v203, v203
	v_fma_f32 v220, v220, v203, v203
	v_fma_f32 v221, v221, v203, v203
	v_fma_f32 v222, v222, v203, v203
	v_fma_f32 v223, v223, v203, v203
	v_fma_f32 v224, v224, v203, v203
	v_fma_f32 v225, v225, v203, v203
	v_rcp_f32_e32 v218, v218
	v_rcp_f32_e32 v219, v219
	v_rcp_f32_e32 v220, v220
	v_rcp_f32_e32 v221, v221
	v_rcp_f32_e32 v222, v222
	v_rcp_f32_e32 v223, v223
	v_rcp_f32_e32 v224, v224
	v_rcp_f32_e32 v225, v225
	v_mul_f32_e32 v210, v210, v218
	v_mul_f32_e32 v211, v211, v219
	v_mul_f32_e32 v212, v212, v220
	v_mul_f32_e32 v213, v213, v221
	v_mul_f32_e32 v214, v214, v222
	v_mul_f32_e32 v215, v215, v223
	v_mul_f32_e32 v216, v216, v224
	v_mul_f32_e32 v217, v217, v225
	v_mul_f32_e32 v116, v210, v116
	v_mul_f32_e32 v117, v211, v117
	v_mul_f32_e32 v118, v212, v118
	v_mul_f32_e32 v119, v213, v119
	v_mul_f32_e32 v112, v214, v112
	v_mul_f32_e32 v113, v215, v113
	v_mul_f32_e32 v114, v216, v114
	v_mul_f32_e32 v115, v217, v115
	v_cvt_pk_bf16_f32 v226, v116, v117
	v_cvt_pk_bf16_f32 v227, v118, v119
	v_cvt_pk_bf16_f32 v228, v112, v113
;     __device__ __forceinline__ void operator()(const Acc& acc, const Unit& u, int wr, int wc, int fr, int fq, LAS unsigned char* lds, f32x4 epar) const {
;     ...
;             for (int m = 0; m < 4; ++m) {
;                 const int r = u.pm * BM + ai * HALF + wr * 64 + m * 16 + fr;
;                 const float rs = __builtin_amdgcn_rsqf(sq[ai][m] * (1.0f / DM) + RMS_EPS);
;                 float X[NV], Y[NV], o[NV];
;                 if (MODE == 0) {
; #pragma unroll
;                     for (int n = 0; n < 2; ++n)
; #pragma unroll
;                         for (int j = 0; j < 4; ++j) { X[n * 4 + j] = acc[ai][0][m][n][j] * rs; Y[n * 4 + j] = acc[ai][1][m][n][j] * rs; }
;                 } else {
; #pragma unroll
;                     for (int j = 0; j < 4; ++j) { X[j] = (acc[ai][0][m][1][j] * rs) * (acc[ai][1][m][0][j] * rs); Y[j] = acc[ai][0][m][0][j] * rs; }
;                 }
; #pragma unroll
;                 for (int i = 0; i < NV; ++i) {
;                     const float a1 = dpp_rot<0x121>(X[i]), a2 = dpp_rot<0x122>(X[i]);
;                     const float q1 = fr >= 1 ? a1 : p1prev[i], q2 = fr >= 2 ? a2 : p2prev[i];
;                     p1prev[i] = a1; p2prev[i] = a2;
;                     const float cv = w2[i] * X[i] + w1[i] * q1 + w0[i] * q2 + bb[i];
;                     o[i] = MODE == 0 ? silu_f(cv) * Y[i] : cv * Y[i];
;                 }
;                 if (m == 0 && fr < 2) {
;                     bf16_t* hx = halo + ((size_t)strip * 6 + 2 + fr) * C + c0; bf16_t* hy = halo + ((size_t)strip * 6 + 4 + fr) * C + c0;
;                     u32x4 px, py; px.x = cvt_pk_bf16(X[0], X[1]); px.y = cvt_pk_bf16(X[2], X[3]); px.z = cvt_pk_bf16(X[4 % NV], X[5 % NV]); px.w = cvt_pk_bf16(X[6 % NV], X[7 % NV]);
;                     py.x = cvt_pk_bf16(Y[0], Y[1]); py.y = cvt_pk_bf16(Y[2], Y[3]); py.z = cvt_pk_bf16(Y[4 % NV], Y[5 % NV]); py.w = cvt_pk_bf16(Y[6 % NV], Y[7 % NV]);
;                     if (MODE == 0) { *(u32x4*)hx = px; *(u32x4*)hy = py; } else { u32x2 a; a.x = px.x; a.y = px.y; *(u32x2*)hx = a; u32x2 b; b.x = py.x; b.y = py.y; *(u32x2*)hy = b; }
;                 } else {
;                     if (MODE == 0) { u32x4 w; w.x = cvt_pk_bf16(o[0], o[1]); w.y = cvt_pk_bf16(o[2], o[3]); w.z = cvt_pk_bf16(o[4 % NV], o[5 % NV]); w.w = cvt_pk_bf16(o[6 % NV], o[7 % NV]);
	v_cvt_pk_bf16_f32 v229, v114, v115
	v_add_u32_e32 v234, 0x16000, v230
	global_store_dwordx4 v234, v[226:229], s[96:97] nt
	v_mul_f32_e32 v108, v108, v184
	v_mul_f32_e32 v109, v109, v184
	v_mul_f32_e32 v110, v110, v184
	v_mul_f32_e32 v111, v111, v184
	v_mul_f32_e32 v104, v104, v184
	v_mul_f32_e32 v105, v105, v184
	v_mul_f32_e32 v106, v106, v184
	v_mul_f32_e32 v107, v107, v184
	v_fma_f32 v210, v108, v136, v174
	v_fma_f32 v211, v109, v137, v175
	v_fma_f32 v212, v110, v138, v176
	v_fma_f32 v213, v111, v139, v177
	v_fma_f32 v214, v104, v140, v178
	v_fma_f32 v215, v105, v141, v179
	v_fma_f32 v216, v106, v142, v180
	v_fma_f32 v217, v107, v143, v181
	v_fmac_f32_dpp v210, v108, v128 row_shr:1 row_mask:0xf bank_mask:0xf
	v_fmac_f32_dpp v211, v109, v129 row_shr:1 row_mask:0xf bank_mask:0xf
	v_fmac_f32_dpp v212, v110, v130 row_shr:1 row_mask:0xf bank_mask:0xf
	v_fmac_f32_dpp v213, v111, v131 row_shr:1 row_mask:0xf bank_mask:0xf
	v_fmac_f32_dpp v214, v104, v132 row_shr:1 row_mask:0xf bank_mask:0xf
	v_fmac_f32_dpp v215, v105, v133 row_shr:1 row_mask:0xf bank_mask:0xf
	v_fmac_f32_dpp v216, v106, v134 row_shr:1 row_mask:0xf bank_mask:0xf
	v_fmac_f32_dpp v217, v107, v135 row_shr:1 row_mask:0xf bank_mask:0xf
	v_fmac_f32_dpp v210, v108, v88 row_shr:2 row_mask:0xf bank_mask:0xf
	v_fmac_f32_dpp v211, v109, v89 row_shr:2 row_mask:0xf bank_mask:0xf
	v_fmac_f32_dpp v212, v110, v90 row_shr:2 row_mask:0xf bank_mask:0xf
	v_fmac_f32_dpp v213, v111, v91 row_shr:2 row_mask:0xf bank_mask:0xf
	v_fmac_f32_dpp v214, v104, v92 row_shr:2 row_mask:0xf bank_mask:0xf
	v_fmac_f32_dpp v215, v105, v93 row_shr:2 row_mask:0xf bank_mask:0xf
	v_fmac_f32_dpp v216, v106, v94 row_shr:2 row_mask:0xf bank_mask:0xf
	v_fmac_f32_dpp v217, v107, v95 row_shr:2 row_mask:0xf bank_mask:0xf
	v_fmac_f32_dpp v210, v124, v128 row_shl:15 row_mask:0xf bank_mask:0xf
	v_fmac_f32_dpp v211, v125, v129 row_shl:15 row_mask:0xf bank_mask:0xf
	v_fmac_f32_dpp v212, v126, v130 row_shl:15 row_mask:0xf bank_mask:0xf
	v_fmac_f32_dpp v213, v127, v131 row_shl:15 row_mask:0xf bank_mask:0xf
	v_fmac_f32_dpp v214, v120, v132 row_shl:15 row_mask:0xf bank_mask:0xf
	v_fmac_f32_dpp v215, v121, v133 row_shl:15 row_mask:0xf bank_mask:0xf
	v_fmac_f32_dpp v216, v122, v134 row_shl:15 row_mask:0xf bank_mask:0xf
	v_fmac_f32_dpp v217, v123, v135 row_shl:15 row_mask:0xf bank_mask:0xf
	v_fmac_f32_dpp v210, v124, v88 row_shl:14 row_mask:0xf bank_mask:0xf
	v_fmac_f32_dpp v211, v125, v89 row_shl:14 row_mask:0xf bank_mask:0xf
	v_fmac_f32_dpp v212, v126, v90 row_shl:14 row_mask:0xf bank_mask:0xf
	v_fmac_f32_dpp v213, v127, v91 row_shl:14 row_mask:0xf bank_mask:0xf
	v_fmac_f32_dpp v214, v120, v92 row_shl:14 row_mask:0xf bank_mask:0xf
	v_fmac_f32_dpp v215, v121, v93 row_shl:14 row_mask:0xf bank_mask:0xf
	v_fmac_f32_dpp v216, v122, v94 row_shl:14 row_mask:0xf bank_mask:0xf
	v_fmac_f32_dpp v217, v123, v95 row_shl:14 row_mask:0xf bank_mask:0xf
	v_exp_f32_e32 v218, v210
	v_exp_f32_e32 v219, v211
	v_exp_f32_e32 v220, v212
	v_exp_f32_e32 v221, v213
	v_exp_f32_e32 v222, v214
	v_exp_f32_e32 v223, v215
	v_exp_f32_e32 v224, v216
	v_exp_f32_e32 v225, v217
	v_fma_f32 v218, v218, v204, v204
	v_fma_f32 v219, v219, v204, v204
	v_fma_f32 v220, v220, v204, v204
	v_fma_f32 v221, v221, v204, v204
	v_fma_f32 v222, v222, v204, v204
	v_fma_f32 v223, v223, v204, v204
	v_fma_f32 v224, v224, v204, v204
	v_fma_f32 v225, v225, v204, v204
	v_rcp_f32_e32 v218, v218
	v_rcp_f32_e32 v219, v219
	v_rcp_f32_e32 v220, v220
	v_rcp_f32_e32 v221, v221
	v_rcp_f32_e32 v222, v222
	v_rcp_f32_e32 v223, v223
	v_rcp_f32_e32 v224, v224
	v_rcp_f32_e32 v225, v225
	v_mul_f32_e32 v210, v210, v218
	v_mul_f32_e32 v211, v211, v219
	v_mul_f32_e32 v212, v212, v220
	v_mul_f32_e32 v213, v213, v221
	v_mul_f32_e32 v214, v214, v222
	v_mul_f32_e32 v215, v215, v223
	v_mul_f32_e32 v216, v216, v224
	v_mul_f32_e32 v217, v217, v225
	v_mul_f32_e32 v100, v210, v100
	v_mul_f32_e32 v101, v211, v101
	v_mul_f32_e32 v102, v212, v102
	v_mul_f32_e32 v103, v213, v103
	v_mul_f32_e32 v96, v214, v96
	v_mul_f32_e32 v97, v215, v97
	v_mul_f32_e32 v98, v216, v98
	v_mul_f32_e32 v99, v217, v99
	v_cvt_pk_bf16_f32 v226, v100, v101
	v_cvt_pk_bf16_f32 v227, v102, v103
	v_cvt_pk_bf16_f32 v228, v96, v97
	v_cvt_pk_bf16_f32 v229, v98, v99
	v_add_u32_e32 v234, 0x2c000, v230
	global_store_dwordx4 v234, v[226:229], s[96:97] nt
	v_mul_f32_e32 v84, v84, v185
	v_mul_f32_e32 v85, v85, v185
	v_mul_f32_e32 v86, v86, v185
	v_mul_f32_e32 v87, v87, v185
	v_mul_f32_e32 v80, v80, v185
	v_mul_f32_e32 v81, v81, v185
	v_mul_f32_e32 v82, v82, v185
	v_mul_f32_e32 v83, v83, v185
	v_fma_f32 v210, v84, v136, v174
	v_fma_f32 v211, v85, v137, v175
	v_fma_f32 v212, v86, v138, v176
	v_fma_f32 v213, v87, v139, v177
	v_fma_f32 v214, v80, v140, v178
	v_fma_f32 v215, v81, v141, v179
	v_fma_f32 v216, v82, v142, v180
	v_fma_f32 v217, v83, v143, v181
	v_cvt_pk_bf16_f32 v236, v84, v85
	v_cvt_pk_bf16_f32 v237, v86, v87
	v_cvt_pk_bf16_f32 v238, v80, v81
	v_cvt_pk_bf16_f32 v239, v82, v83
	v_add_u32_e32 v235, 0xfffecc00, v233
	s_and_b64 exec, exec, s[10:11]
	global_store_dwordx4 v235, v[236:239], s[42:43]
	s_mov_b64 exec, s[24:25]
	v_fmac_f32_dpp v210, v84, v128 row_shr:1 row_mask:0xf bank_mask:0xf
	v_fmac_f32_dpp v211, v85, v129 row_shr:1 row_mask:0xf bank_mask:0xf
	v_fmac_f32_dpp v212, v86, v130 row_shr:1 row_mask:0xf bank_mask:0xf
	v_fmac_f32_dpp v213, v87, v131 row_shr:1 row_mask:0xf bank_mask:0xf
	v_fmac_f32_dpp v214, v80, v132 row_shr:1 row_mask:0xf bank_mask:0xf
	v_fmac_f32_dpp v215, v81, v133 row_shr:1 row_mask:0xf bank_mask:0xf
	v_fmac_f32_dpp v216, v82, v134 row_shr:1 row_mask:0xf bank_mask:0xf
	v_fmac_f32_dpp v217, v83, v135 row_shr:1 row_mask:0xf bank_mask:0xf
;     __device__ __forceinline__ void operator()(const Acc& acc, const Unit& u, int wr, int wc, int fr, int fq, LAS unsigned char* lds, f32x4 epar) const {
;     ...
;             for (int m = 0; m < 4; ++m) {
;                 const int r = u.pm * BM + ai * HALF + wr * 64 + m * 16 + fr;
;                 const float rs = __builtin_amdgcn_rsqf(sq[ai][m] * (1.0f / DM) + RMS_EPS);
;                 float X[NV], Y[NV], o[NV];
;                 if (MODE == 0) {
; #pragma unroll
;                     for (int n = 0; n < 2; ++n)
; #pragma unroll
;                         for (int j = 0; j < 4; ++j) { X[n * 4 + j] = acc[ai][0][m][n][j] * rs; Y[n * 4 + j] = acc[ai][1][m][n][j] * rs; }
;                 } else {
; #pragma unroll
;                     for (int j = 0; j < 4; ++j) { X[j] = (acc[ai][0][m][1][j] * rs) * (acc[ai][1][m][0][j] * rs); Y[j] = acc[ai][0][m][0][j] * rs; }
;                 }
; #pragma unroll
;                 for (int i = 0; i < NV; ++i) {
;                     const float a1 = dpp_rot<0x121>(X[i]), a2 = dpp_rot<0x122>(X[i]);
;                     const float q1 = fr >= 1 ? a1 : p1prev[i], q2 = fr >= 2 ? a2 : p2prev[i];
;                     p1prev[i] = a1; p2prev[i] = a2;
;                     const float cv = w2[i] * X[i] + w1[i] * q1 + w0[i] * q2 + bb[i];
;                     o[i] = MODE == 0 ? silu_f(cv) * Y[i] : cv * Y[i];
;                 }
;                 if (m == 0 && fr < 2) {
;                     bf16_t* hx = halo + ((size_t)strip * 6 + 2 + fr) * C + c0; bf16_t* hy = halo + ((size_t)strip * 6 + 4 + fr) * C + c0;
;                     u32x4 px, py; px.x = cvt_pk_bf16(X[0], X[1]); px.y = cvt_pk_bf16(X[2], X[3]); px.z = cvt_pk_bf16(X[4 % NV], X[5 % NV]); px.w = cvt_pk_bf16(X[6 % NV], X[7 % NV]);
;                     py.x = cvt_pk_bf16(Y[0], Y[1]); py.y = cvt_pk_bf16(Y[2], Y[3]); py.z = cvt_pk_bf16(Y[4 % NV], Y[5 % NV]); py.w = cvt_pk_bf16(Y[6 % NV], Y[7 % NV]);
;                     if (MODE == 0) { *(u32x4*)hx = px; *(u32x4*)hy = py; } else { u32x2 a; a.x = px.x; a.y = px.y; *(u32x2*)hx = a; u32x2 b; b.x = py.x; b.y = py.y; *(u32x2*)hy = b; }
;                 } else {
;                     if (MODE == 0) { u32x4 w; w.x = cvt_pk_bf16(o[0], o[1]); w.y = cvt_pk_bf16(o[2], o[3]); w.z = cvt_pk_bf16(o[4 % NV], o[5 % NV]); w.w = cvt_pk_bf16(o[6 % NV], o[7 % NV]);
	v_fmac_f32_dpp v210, v84, v88 row_shr:2 row_mask:0xf bank_mask:0xf
	v_fmac_f32_dpp v211, v85, v89 row_shr:2 row_mask:0xf bank_mask:0xf
	v_fmac_f32_dpp v212, v86, v90 row_shr:2 row_mask:0xf bank_mask:0xf
	v_fmac_f32_dpp v213, v87, v91 row_shr:2 row_mask:0xf bank_mask:0xf
	v_fmac_f32_dpp v214, v80, v92 row_shr:2 row_mask:0xf bank_mask:0xf
	v_fmac_f32_dpp v215, v81, v93 row_shr:2 row_mask:0xf bank_mask:0xf
	v_fmac_f32_dpp v216, v82, v94 row_shr:2 row_mask:0xf bank_mask:0xf
	v_fmac_f32_dpp v217, v83, v95 row_shr:2 row_mask:0xf bank_mask:0xf
	v_fmac_f32_dpp v210, v108, v128 row_shl:15 row_mask:0xf bank_mask:0xf
	v_fmac_f32_dpp v211, v109, v129 row_shl:15 row_mask:0xf bank_mask:0xf
	v_fmac_f32_dpp v212, v110, v130 row_shl:15 row_mask:0xf bank_mask:0xf
	v_fmac_f32_dpp v213, v111, v131 row_shl:15 row_mask:0xf bank_mask:0xf
	v_fmac_f32_dpp v214, v104, v132 row_shl:15 row_mask:0xf bank_mask:0xf
	v_fmac_f32_dpp v215, v105, v133 row_shl:15 row_mask:0xf bank_mask:0xf
	v_fmac_f32_dpp v216, v106, v134 row_shl:15 row_mask:0xf bank_mask:0xf
	v_fmac_f32_dpp v217, v107, v135 row_shl:15 row_mask:0xf bank_mask:0xf
	v_fmac_f32_dpp v210, v108, v88 row_shl:14 row_mask:0xf bank_mask:0xf
	v_fmac_f32_dpp v211, v109, v89 row_shl:14 row_mask:0xf bank_mask:0xf
	v_fmac_f32_dpp v212, v110, v90 row_shl:14 row_mask:0xf bank_mask:0xf
	v_fmac_f32_dpp v213, v111, v91 row_shl:14 row_mask:0xf bank_mask:0xf
	v_fmac_f32_dpp v214, v104, v92 row_shl:14 row_mask:0xf bank_mask:0xf
	v_fmac_f32_dpp v215, v105, v93 row_shl:14 row_mask:0xf bank_mask:0xf
	v_fmac_f32_dpp v216, v106, v94 row_shl:14 row_mask:0xf bank_mask:0xf
	v_fmac_f32_dpp v217, v107, v95 row_shl:14 row_mask:0xf bank_mask:0xf
	v_exp_f32_e32 v218, v210
	v_exp_f32_e32 v219, v211
	v_exp_f32_e32 v220, v212
	v_exp_f32_e32 v221, v213
	v_exp_f32_e32 v222, v214
	v_exp_f32_e32 v223, v215
	v_exp_f32_e32 v224, v216
	v_exp_f32_e32 v225, v217
	v_fma_f32 v218, v218, v205, v205
	v_fma_f32 v219, v219, v205, v205
	v_fma_f32 v220, v220, v205, v205
	v_fma_f32 v221, v221, v205, v205
	v_fma_f32 v222, v222, v205, v205
	v_fma_f32 v223, v223, v205, v205
	v_fma_f32 v224, v224, v205, v205
	v_fma_f32 v225, v225, v205, v205
	v_rcp_f32_e32 v218, v218
	v_rcp_f32_e32 v219, v219
	v_rcp_f32_e32 v220, v220
	v_rcp_f32_e32 v221, v221
	v_rcp_f32_e32 v222, v222
	v_rcp_f32_e32 v223, v223
	v_rcp_f32_e32 v224, v224
	v_rcp_f32_e32 v225, v225
	v_mul_f32_e32 v210, v210, v218
	v_mul_f32_e32 v211, v211, v219
	v_mul_f32_e32 v212, v212, v220
	v_mul_f32_e32 v213, v213, v221
	v_mul_f32_e32 v214, v214, v222
	v_mul_f32_e32 v215, v215, v223
	v_mul_f32_e32 v216, v216, v224
	v_mul_f32_e32 v217, v217, v225
	v_mul_f32_e32 v68, v210, v68
	v_mul_f32_e32 v69, v211, v69
	v_mul_f32_e32 v70, v212, v70
	v_mul_f32_e32 v71, v213, v71
	v_mul_f32_e32 v64, v214, v64
	v_mul_f32_e32 v65, v215, v65
	v_mul_f32_e32 v66, v216, v66
	v_mul_f32_e32 v67, v217, v67
	v_cvt_pk_bf16_f32 v226, v68, v69
	v_cvt_pk_bf16_f32 v227, v70, v71
	v_cvt_pk_bf16_f32 v228, v64, v65
	v_cvt_pk_bf16_f32 v229, v66, v67
	v_add_u32_e32 v234, 0x42000, v230
	global_store_dwordx4 v234, v[226:229], s[96:97] nt
	v_mul_f32_e32 v60, v60, v76
	v_mul_f32_e32 v61, v61, v76
	v_mul_f32_e32 v62, v62, v76
	v_mul_f32_e32 v63, v63, v76
	v_mul_f32_e32 v52, v52, v76
	v_mul_f32_e32 v53, v53, v76
	v_mul_f32_e32 v54, v54, v76
	v_mul_f32_e32 v55, v55, v76
	v_fma_f32 v210, v60, v136, v174
	v_fma_f32 v211, v61, v137, v175
	v_fma_f32 v212, v62, v138, v176
	v_fma_f32 v213, v63, v139, v177
	v_fma_f32 v214, v52, v140, v178
	v_fma_f32 v215, v53, v141, v179
	v_fma_f32 v216, v54, v142, v180
	v_fma_f32 v217, v55, v143, v181
	v_mul_f32_e32 v218, v56, v76
	v_mul_f32_e32 v219, v57, v76
	v_mul_f32_e32 v220, v58, v76
	v_mul_f32_e32 v221, v59, v76
	v_mul_f32_e32 v222, v48, v76
	v_mul_f32_e32 v223, v49, v76
	v_mul_f32_e32 v224, v50, v76
	v_mul_f32_e32 v225, v51, v76
	v_cvt_pk_bf16_f32 v236, v60, v61
	v_cvt_pk_bf16_f32 v237, v62, v63
	v_cvt_pk_bf16_f32 v238, v52, v53
	v_cvt_pk_bf16_f32 v239, v54, v55
	v_cvt_pk_bf16_f32 v240, v218, v219
	v_cvt_pk_bf16_f32 v241, v220, v221
	v_cvt_pk_bf16_f32 v242, v222, v223
	v_cvt_pk_bf16_f32 v243, v224, v225
	v_add_u32_e32 v234, 0x13400, v233
	v_add_u32_e32 v235, 0x16000, v233
	s_andn2_b64 exec, exec, s[8:9]
	global_store_dwordx4 v234, v[236:239], s[42:43]
	global_store_dwordx4 v235, v[240:243], s[42:43]
	s_mov_b64 exec, s[24:25]
	v_fmac_f32_dpp v210, v60, v128 row_shr:1 row_mask:0xf bank_mask:0xf
	v_fmac_f32_dpp v211, v61, v129 row_shr:1 row_mask:0xf bank_mask:0xf
	v_fmac_f32_dpp v212, v62, v130 row_shr:1 row_mask:0xf bank_mask:0xf
	v_fmac_f32_dpp v213, v63, v131 row_shr:1 row_mask:0xf bank_mask:0xf
	v_fmac_f32_dpp v214, v52, v132 row_shr:1 row_mask:0xf bank_mask:0xf
	v_fmac_f32_dpp v215, v53, v133 row_shr:1 row_mask:0xf bank_mask:0xf
	v_fmac_f32_dpp v216, v54, v134 row_shr:1 row_mask:0xf bank_mask:0xf
	v_fmac_f32_dpp v217, v55, v135 row_shr:1 row_mask:0xf bank_mask:0xf
	v_fmac_f32_dpp v210, v60, v88 row_shr:2 row_mask:0xf bank_mask:0xf
	v_fmac_f32_dpp v211, v61, v89 row_shr:2 row_mask:0xf bank_mask:0xf
	v_fmac_f32_dpp v212, v62, v90 row_shr:2 row_mask:0xf bank_mask:0xf
	v_fmac_f32_dpp v213, v63, v91 row_shr:2 row_mask:0xf bank_mask:0xf
	v_fmac_f32_dpp v214, v52, v92 row_shr:2 row_mask:0xf bank_mask:0xf
	v_fmac_f32_dpp v215, v53, v93 row_shr:2 row_mask:0xf bank_mask:0xf
	v_fmac_f32_dpp v216, v54, v94 row_shr:2 row_mask:0xf bank_mask:0xf
	v_fmac_f32_dpp v217, v55, v95 row_shr:2 row_mask:0xf bank_mask:0xf
	v_exp_f32_e32 v218, v210
	v_exp_f32_e32 v219, v211
	v_exp_f32_e32 v220, v212
	v_exp_f32_e32 v221, v213
	v_exp_f32_e32 v222, v214
	v_exp_f32_e32 v223, v215
	v_exp_f32_e32 v224, v216
	v_exp_f32_e32 v225, v217
;     __device__ __forceinline__ void operator()(const Acc& acc, const Unit& u, int wr, int wc, int fr, int fq, LAS unsigned char* lds, f32x4 epar) const {
;     ...
;             for (int m = 0; m < 4; ++m) {
;                 const int r = u.pm * BM + ai * HALF + wr * 64 + m * 16 + fr;
;                 const float rs = __builtin_amdgcn_rsqf(sq[ai][m] * (1.0f / DM) + RMS_EPS);
;                 float X[NV], Y[NV], o[NV];
;                 if (MODE == 0) {
; #pragma unroll
;                     for (int n = 0; n < 2; ++n)
; #pragma unroll
;                         for (int j = 0; j < 4; ++j) { X[n * 4 + j] = acc[ai][0][m][n][j] * rs; Y[n * 4 + j] = acc[ai][1][m][n][j] * rs; }
;                 } else {
; #pragma unroll
;                     for (int j = 0; j < 4; ++j) { X[j] = (acc[ai][0][m][1][j] * rs) * (acc[ai][1][m][0][j] * rs); Y[j] = acc[ai][0][m][0][j] * rs; }
;                 }
; #pragma unroll
;                 for (int i = 0; i < NV; ++i) {
;                     const float a1 = dpp_rot<0x121>(X[i]), a2 = dpp_rot<0x122>(X[i]);
;                     const float q1 = fr >= 1 ? a1 : p1prev[i], q2 = fr >= 2 ? a2 : p2prev[i];
;                     p1prev[i] = a1; p2prev[i] = a2;
;                     const float cv = w2[i] * X[i] + w1[i] * q1 + w0[i] * q2 + bb[i];
;                     o[i] = MODE == 0 ? silu_f(cv) * Y[i] : cv * Y[i];
;                 }
;                 if (m == 0 && fr < 2) {
;                     bf16_t* hx = halo + ((size_t)strip * 6 + 2 + fr) * C + c0; bf16_t* hy = halo + ((size_t)strip * 6 + 4 + fr) * C + c0;
;                     u32x4 px, py; px.x = cvt_pk_bf16(X[0], X[1]); px.y = cvt_pk_bf16(X[2], X[3]); px.z = cvt_pk_bf16(X[4 % NV], X[5 % NV]); px.w = cvt_pk_bf16(X[6 % NV], X[7 % NV]);
;                     py.x = cvt_pk_bf16(Y[0], Y[1]); py.y = cvt_pk_bf16(Y[2], Y[3]); py.z = cvt_pk_bf16(Y[4 % NV], Y[5 % NV]); py.w = cvt_pk_bf16(Y[6 % NV], Y[7 % NV]);
;                     if (MODE == 0) { *(u32x4*)hx = px; *(u32x4*)hy = py; } else { u32x2 a; a.x = px.x; a.y = px.y; *(u32x2*)hx = a; u32x2 b; b.x = py.x; b.y = py.y; *(u32x2*)hy = b; }
;                 } else {
;                     if (MODE == 0) { u32x4 w; w.x = cvt_pk_bf16(o[0], o[1]); w.y = cvt_pk_bf16(o[2], o[3]); w.z = cvt_pk_bf16(o[4 % NV], o[5 % NV]); w.w = cvt_pk_bf16(o[6 % NV], o[7 % NV]);
	v_fma_f32 v218, v218, v206, v206
	v_fma_f32 v219, v219, v206, v206
	v_fma_f32 v220, v220, v206, v206
	v_fma_f32 v221, v221, v206, v206
	v_fma_f32 v222, v222, v206, v206
	v_fma_f32 v223, v223, v206, v206
	v_fma_f32 v224, v224, v206, v206
	v_fma_f32 v225, v225, v206, v206
	v_rcp_f32_e32 v218, v218
	v_rcp_f32_e32 v219, v219
	v_rcp_f32_e32 v220, v220
	v_rcp_f32_e32 v221, v221
	v_rcp_f32_e32 v222, v222
	v_rcp_f32_e32 v223, v223
	v_rcp_f32_e32 v224, v224
	v_rcp_f32_e32 v225, v225
	v_mul_f32_e32 v210, v210, v218
	v_mul_f32_e32 v211, v211, v219
	v_mul_f32_e32 v212, v212, v220
	v_mul_f32_e32 v213, v213, v221
	v_mul_f32_e32 v214, v214, v222
	v_mul_f32_e32 v215, v215, v223
	v_mul_f32_e32 v216, v216, v224
	v_mul_f32_e32 v217, v217, v225
	v_mul_f32_e32 v56, v210, v56
	v_mul_f32_e32 v57, v211, v57
	v_mul_f32_e32 v58, v212, v58
	v_mul_f32_e32 v59, v213, v59
	v_mul_f32_e32 v48, v214, v48
	v_mul_f32_e32 v49, v215, v49
	v_mul_f32_e32 v50, v216, v50
	v_mul_f32_e32 v51, v217, v51
	v_cvt_pk_bf16_f32 v226, v56, v57
	v_cvt_pk_bf16_f32 v227, v58, v59
	v_cvt_pk_bf16_f32 v228, v48, v49
	v_cvt_pk_bf16_f32 v229, v50, v51
	v_add_u32_e32 v234, 0xb0000, v230
	s_and_b64 exec, exec, s[8:9]
	global_store_dwordx4 v234, v[226:229], s[96:97] nt
	s_mov_b64 exec, s[24:25]
	v_mul_f32_e32 v44, v44, v77
	v_mul_f32_e32 v45, v45, v77
	v_mul_f32_e32 v46, v46, v77
	v_mul_f32_e32 v47, v47, v77
	v_mul_f32_e32 v40, v40, v77
	v_mul_f32_e32 v41, v41, v77
	v_mul_f32_e32 v42, v42, v77
	v_mul_f32_e32 v43, v43, v77
	v_fma_f32 v210, v44, v136, v174
	v_fma_f32 v211, v45, v137, v175
	v_fma_f32 v212, v46, v138, v176
	v_fma_f32 v213, v47, v139, v177
	v_fma_f32 v214, v40, v140, v178
	v_fma_f32 v215, v41, v141, v179
	v_fma_f32 v216, v42, v142, v180
	v_fma_f32 v217, v43, v143, v181
	v_fmac_f32_dpp v210, v44, v128 row_shr:1 row_mask:0xf bank_mask:0xf
	v_fmac_f32_dpp v211, v45, v129 row_shr:1 row_mask:0xf bank_mask:0xf
	v_fmac_f32_dpp v212, v46, v130 row_shr:1 row_mask:0xf bank_mask:0xf
	v_fmac_f32_dpp v213, v47, v131 row_shr:1 row_mask:0xf bank_mask:0xf
	v_fmac_f32_dpp v214, v40, v132 row_shr:1 row_mask:0xf bank_mask:0xf
	v_fmac_f32_dpp v215, v41, v133 row_shr:1 row_mask:0xf bank_mask:0xf
	v_fmac_f32_dpp v216, v42, v134 row_shr:1 row_mask:0xf bank_mask:0xf
	v_fmac_f32_dpp v217, v43, v135 row_shr:1 row_mask:0xf bank_mask:0xf
	v_fmac_f32_dpp v210, v44, v88 row_shr:2 row_mask:0xf bank_mask:0xf
	v_fmac_f32_dpp v211, v45, v89 row_shr:2 row_mask:0xf bank_mask:0xf
	v_fmac_f32_dpp v212, v46, v90 row_shr:2 row_mask:0xf bank_mask:0xf
	v_fmac_f32_dpp v213, v47, v91 row_shr:2 row_mask:0xf bank_mask:0xf
	v_fmac_f32_dpp v214, v40, v92 row_shr:2 row_mask:0xf bank_mask:0xf
	v_fmac_f32_dpp v215, v41, v93 row_shr:2 row_mask:0xf bank_mask:0xf
	v_fmac_f32_dpp v216, v42, v94 row_shr:2 row_mask:0xf bank_mask:0xf
	v_fmac_f32_dpp v217, v43, v95 row_shr:2 row_mask:0xf bank_mask:0xf
	v_fmac_f32_dpp v210, v60, v128 row_shl:15 row_mask:0xf bank_mask:0xf
	v_fmac_f32_dpp v211, v61, v129 row_shl:15 row_mask:0xf bank_mask:0xf
	v_fmac_f32_dpp v212, v62, v130 row_shl:15 row_mask:0xf bank_mask:0xf
	v_fmac_f32_dpp v213, v63, v131 row_shl:15 row_mask:0xf bank_mask:0xf
	v_fmac_f32_dpp v214, v52, v132 row_shl:15 row_mask:0xf bank_mask:0xf
	v_fmac_f32_dpp v215, v53, v133 row_shl:15 row_mask:0xf bank_mask:0xf
	v_fmac_f32_dpp v216, v54, v134 row_shl:15 row_mask:0xf bank_mask:0xf
	v_fmac_f32_dpp v217, v55, v135 row_shl:15 row_mask:0xf bank_mask:0xf
	v_fmac_f32_dpp v210, v60, v88 row_shl:14 row_mask:0xf bank_mask:0xf
	v_fmac_f32_dpp v211, v61, v89 row_shl:14 row_mask:0xf bank_mask:0xf
	v_fmac_f32_dpp v212, v62, v90 row_shl:14 row_mask:0xf bank_mask:0xf
	v_fmac_f32_dpp v213, v63, v91 row_shl:14 row_mask:0xf bank_mask:0xf
	v_fmac_f32_dpp v214, v52, v92 row_shl:14 row_mask:0xf bank_mask:0xf
	v_fmac_f32_dpp v215, v53, v93 row_shl:14 row_mask:0xf bank_mask:0xf
	v_fmac_f32_dpp v216, v54, v94 row_shl:14 row_mask:0xf bank_mask:0xf
	v_fmac_f32_dpp v217, v55, v95 row_shl:14 row_mask:0xf bank_mask:0xf
	v_exp_f32_e32 v218, v210
	v_exp_f32_e32 v219, v211
	v_exp_f32_e32 v220, v212
	v_exp_f32_e32 v221, v213
	v_exp_f32_e32 v222, v214
	v_exp_f32_e32 v223, v215
	v_exp_f32_e32 v224, v216
	v_exp_f32_e32 v225, v217
	v_fma_f32 v218, v218, v207, v207
	v_fma_f32 v219, v219, v207, v207
	v_fma_f32 v220, v220, v207, v207
	v_fma_f32 v221, v221, v207, v207
	v_fma_f32 v222, v222, v207, v207
	v_fma_f32 v223, v223, v207, v207
	v_fma_f32 v224, v224, v207, v207
	v_fma_f32 v225, v225, v207, v207
	v_rcp_f32_e32 v218, v218
	v_rcp_f32_e32 v219, v219
	v_rcp_f32_e32 v220, v220
	v_rcp_f32_e32 v221, v221
	v_rcp_f32_e32 v222, v222
	v_rcp_f32_e32 v223, v223
	v_rcp_f32_e32 v224, v224
	v_rcp_f32_e32 v225, v225
	v_mul_f32_e32 v210, v210, v218
	v_mul_f32_e32 v211, v211, v219
	v_mul_f32_e32 v212, v212, v220
	v_mul_f32_e32 v213, v213, v221
	v_mul_f32_e32 v214, v214, v222
	v_mul_f32_e32 v215, v215, v223
	v_mul_f32_e32 v216, v216, v224
	v_mul_f32_e32 v217, v217, v225
	v_mul_f32_e32 v36, v210, v36
	v_mul_f32_e32 v37, v211, v37
	v_mul_f32_e32 v38, v212, v38
	v_mul_f32_e32 v39, v213, v39
	v_mul_f32_e32 v32, v214, v32
	v_mul_f32_e32 v33, v215, v33
	v_mul_f32_e32 v34, v216, v34
	v_mul_f32_e32 v35, v217, v35
	v_cvt_pk_bf16_f32 v226, v36, v37
	v_cvt_pk_bf16_f32 v227, v38, v39
	v_cvt_pk_bf16_f32 v228, v32, v33
	v_cvt_pk_bf16_f32 v229, v34, v35
	v_add_u32_e32 v234, 0xc6000, v230
	global_store_dwordx4 v234, v[226:229], s[96:97] nt
	v_mul_f32_e32 v28, v28, v78
	v_mul_f32_e32 v29, v29, v78
	v_mul_f32_e32 v30, v30, v78
	v_mul_f32_e32 v31, v31, v78
	v_mul_f32_e32 v24, v24, v78
	v_mul_f32_e32 v25, v25, v78
	v_mul_f32_e32 v26, v26, v78
	v_mul_f32_e32 v27, v27, v78
	v_fma_f32 v210, v28, v136, v174
;     __device__ __forceinline__ void operator()(const Acc& acc, const Unit& u, int wr, int wc, int fr, int fq, LAS unsigned char* lds, f32x4 epar) const {
;     ...
;             for (int m = 0; m < 4; ++m) {
;                 const int r = u.pm * BM + ai * HALF + wr * 64 + m * 16 + fr;
;                 const float rs = __builtin_amdgcn_rsqf(sq[ai][m] * (1.0f / DM) + RMS_EPS);
;                 float X[NV], Y[NV], o[NV];
;                 if (MODE == 0) {
; #pragma unroll
;                     for (int n = 0; n < 2; ++n)
; #pragma unroll
;                         for (int j = 0; j < 4; ++j) { X[n * 4 + j] = acc[ai][0][m][n][j] * rs; Y[n * 4 + j] = acc[ai][1][m][n][j] * rs; }
;                 } else {
; #pragma unroll
;                     for (int j = 0; j < 4; ++j) { X[j] = (acc[ai][0][m][1][j] * rs) * (acc[ai][1][m][0][j] * rs); Y[j] = acc[ai][0][m][0][j] * rs; }
;                 }
; #pragma unroll
;                 for (int i = 0; i < NV; ++i) {
;                     const float a1 = dpp_rot<0x121>(X[i]), a2 = dpp_rot<0x122>(X[i]);
;                     const float q1 = fr >= 1 ? a1 : p1prev[i], q2 = fr >= 2 ? a2 : p2prev[i];
;                     p1prev[i] = a1; p2prev[i] = a2;
;                     const float cv = w2[i] * X[i] + w1[i] * q1 + w0[i] * q2 + bb[i];
;                     o[i] = MODE == 0 ? silu_f(cv) * Y[i] : cv * Y[i];
;                 }
;                 if (m == 0 && fr < 2) {
;                     bf16_t* hx = halo + ((size_t)strip * 6 + 2 + fr) * C + c0; bf16_t* hy = halo + ((size_t)strip * 6 + 4 + fr) * C + c0;
;                     u32x4 px, py; px.x = cvt_pk_bf16(X[0], X[1]); px.y = cvt_pk_bf16(X[2], X[3]); px.z = cvt_pk_bf16(X[4 % NV], X[5 % NV]); px.w = cvt_pk_bf16(X[6 % NV], X[7 % NV]);
;                     py.x = cvt_pk_bf16(Y[0], Y[1]); py.y = cvt_pk_bf16(Y[2], Y[3]); py.z = cvt_pk_bf16(Y[4 % NV], Y[5 % NV]); py.w = cvt_pk_bf16(Y[6 % NV], Y[7 % NV]);
;                     if (MODE == 0) { *(u32x4*)hx = px; *(u32x4*)hy = py; } else { u32x2 a; a.x = px.x; a.y = px.y; *(u32x2*)hx = a; u32x2 b; b.x = py.x; b.y = py.y; *(u32x2*)hy = b; }
;                 } else {
;                     if (MODE == 0) { u32x4 w; w.x = cvt_pk_bf16(o[0], o[1]); w.y = cvt_pk_bf16(o[2], o[3]); w.z = cvt_pk_bf16(o[4 % NV], o[5 % NV]); w.w = cvt_pk_bf16(o[6 % NV], o[7 % NV]);
	v_fma_f32 v211, v29, v137, v175
	v_fma_f32 v212, v30, v138, v176
	v_fma_f32 v213, v31, v139, v177
	v_fma_f32 v214, v24, v140, v178
	v_fma_f32 v215, v25, v141, v179
	v_fma_f32 v216, v26, v142, v180
	v_fma_f32 v217, v27, v143, v181
	v_fmac_f32_dpp v210, v28, v128 row_shr:1 row_mask:0xf bank_mask:0xf
	v_fmac_f32_dpp v211, v29, v129 row_shr:1 row_mask:0xf bank_mask:0xf
	v_fmac_f32_dpp v212, v30, v130 row_shr:1 row_mask:0xf bank_mask:0xf
	v_fmac_f32_dpp v213, v31, v131 row_shr:1 row_mask:0xf bank_mask:0xf
	v_fmac_f32_dpp v214, v24, v132 row_shr:1 row_mask:0xf bank_mask:0xf
	v_fmac_f32_dpp v215, v25, v133 row_shr:1 row_mask:0xf bank_mask:0xf
	v_fmac_f32_dpp v216, v26, v134 row_shr:1 row_mask:0xf bank_mask:0xf
	v_fmac_f32_dpp v217, v27, v135 row_shr:1 row_mask:0xf bank_mask:0xf
	v_fmac_f32_dpp v210, v28, v88 row_shr:2 row_mask:0xf bank_mask:0xf
	v_fmac_f32_dpp v211, v29, v89 row_shr:2 row_mask:0xf bank_mask:0xf
	v_fmac_f32_dpp v212, v30, v90 row_shr:2 row_mask:0xf bank_mask:0xf
	v_fmac_f32_dpp v213, v31, v91 row_shr:2 row_mask:0xf bank_mask:0xf
	v_fmac_f32_dpp v214, v24, v92 row_shr:2 row_mask:0xf bank_mask:0xf
	v_fmac_f32_dpp v215, v25, v93 row_shr:2 row_mask:0xf bank_mask:0xf
	v_fmac_f32_dpp v216, v26, v94 row_shr:2 row_mask:0xf bank_mask:0xf
	v_fmac_f32_dpp v217, v27, v95 row_shr:2 row_mask:0xf bank_mask:0xf
	v_fmac_f32_dpp v210, v44, v128 row_shl:15 row_mask:0xf bank_mask:0xf
	v_fmac_f32_dpp v211, v45, v129 row_shl:15 row_mask:0xf bank_mask:0xf
	v_fmac_f32_dpp v212, v46, v130 row_shl:15 row_mask:0xf bank_mask:0xf
	v_fmac_f32_dpp v213, v47, v131 row_shl:15 row_mask:0xf bank_mask:0xf
	v_fmac_f32_dpp v214, v40, v132 row_shl:15 row_mask:0xf bank_mask:0xf
	v_fmac_f32_dpp v215, v41, v133 row_shl:15 row_mask:0xf bank_mask:0xf
	v_fmac_f32_dpp v216, v42, v134 row_shl:15 row_mask:0xf bank_mask:0xf
	v_fmac_f32_dpp v217, v43, v135 row_shl:15 row_mask:0xf bank_mask:0xf
	v_fmac_f32_dpp v210, v44, v88 row_shl:14 row_mask:0xf bank_mask:0xf
	v_fmac_f32_dpp v211, v45, v89 row_shl:14 row_mask:0xf bank_mask:0xf
	v_fmac_f32_dpp v212, v46, v90 row_shl:14 row_mask:0xf bank_mask:0xf
	v_fmac_f32_dpp v213, v47, v91 row_shl:14 row_mask:0xf bank_mask:0xf
	v_fmac_f32_dpp v214, v40, v92 row_shl:14 row_mask:0xf bank_mask:0xf
	v_fmac_f32_dpp v215, v41, v93 row_shl:14 row_mask:0xf bank_mask:0xf
	v_fmac_f32_dpp v216, v42, v94 row_shl:14 row_mask:0xf bank_mask:0xf
	v_fmac_f32_dpp v217, v43, v95 row_shl:14 row_mask:0xf bank_mask:0xf
	v_exp_f32_e32 v218, v210
	v_exp_f32_e32 v219, v211
	v_exp_f32_e32 v220, v212
	v_exp_f32_e32 v221, v213
	v_exp_f32_e32 v222, v214
	v_exp_f32_e32 v223, v215
	v_exp_f32_e32 v224, v216
	v_exp_f32_e32 v225, v217
	v_fma_f32 v218, v218, v208, v208
	v_fma_f32 v219, v219, v208, v208
	v_fma_f32 v220, v220, v208, v208
	v_fma_f32 v221, v221, v208, v208
	v_fma_f32 v222, v222, v208, v208
	v_fma_f32 v223, v223, v208, v208
	v_fma_f32 v224, v224, v208, v208
	v_fma_f32 v225, v225, v208, v208
	v_rcp_f32_e32 v218, v218
	v_rcp_f32_e32 v219, v219
	v_rcp_f32_e32 v220, v220
	v_rcp_f32_e32 v221, v221
	v_rcp_f32_e32 v222, v222
	v_rcp_f32_e32 v223, v223
	v_rcp_f32_e32 v224, v224
	v_rcp_f32_e32 v225, v225
	v_mul_f32_e32 v210, v210, v218
	v_mul_f32_e32 v211, v211, v219
	v_mul_f32_e32 v212, v212, v220
	v_mul_f32_e32 v213, v213, v221
	v_mul_f32_e32 v214, v214, v222
	v_mul_f32_e32 v215, v215, v223
	v_mul_f32_e32 v216, v216, v224
	v_mul_f32_e32 v217, v217, v225
	v_mul_f32_e32 v20, v210, v20
	v_mul_f32_e32 v21, v211, v21
	v_mul_f32_e32 v22, v212, v22
	v_mul_f32_e32 v23, v213, v23
	v_mul_f32_e32 v16, v214, v16
	v_mul_f32_e32 v17, v215, v17
	v_mul_f32_e32 v18, v216, v18
	v_mul_f32_e32 v19, v217, v19
	v_cvt_pk_bf16_f32 v226, v20, v21
	v_cvt_pk_bf16_f32 v227, v22, v23
	v_cvt_pk_bf16_f32 v228, v16, v17
	v_cvt_pk_bf16_f32 v229, v18, v19
	v_add_u32_e32 v234, 0xdc000, v230
	global_store_dwordx4 v234, v[226:229], s[96:97] nt
	v_mul_f32_e32 v12, v12, v79
	v_mul_f32_e32 v13, v13, v79
	v_mul_f32_e32 v14, v14, v79
	v_mul_f32_e32 v15, v15, v79
	v_mul_f32_e32 v8, v8, v79
	v_mul_f32_e32 v9, v9, v79
	v_mul_f32_e32 v10, v10, v79
	v_mul_f32_e32 v11, v11, v79
	v_fma_f32 v210, v12, v136, v174
;     __device__ __forceinline__ void operator()(const Acc& acc, const Unit& u, int wr, int wc, int fr, int fq, LAS unsigned char* lds, f32x4 epar) const {
;     ...
;             for (int m = 0; m < 4; ++m) {
;                 const int r = u.pm * BM + ai * HALF + wr * 64 + m * 16 + fr;
;                 const float rs = __builtin_amdgcn_rsqf(sq[ai][m] * (1.0f / DM) + RMS_EPS);
;                 float X[NV], Y[NV], o[NV];
;                 if (MODE == 0) {
; #pragma unroll
;                     for (int n = 0; n < 2; ++n)
; #pragma unroll
;                         for (int j = 0; j < 4; ++j) { X[n * 4 + j] = acc[ai][0][m][n][j] * rs; Y[n * 4 + j] = acc[ai][1][m][n][j] * rs; }
;                 } else {
; #pragma unroll
;                     for (int j = 0; j < 4; ++j) { X[j] = (acc[ai][0][m][1][j] * rs) * (acc[ai][1][m][0][j] * rs); Y[j] = acc[ai][0][m][0][j] * rs; }
;                 }
; #pragma unroll
;                 for (int i = 0; i < NV; ++i) {
;                     const float a1 = dpp_rot<0x121>(X[i]), a2 = dpp_rot<0x122>(X[i]);
;                     const float q1 = fr >= 1 ? a1 : p1prev[i], q2 = fr >= 2 ? a2 : p2prev[i];
;                     p1prev[i] = a1; p2prev[i] = a2;
;                     const float cv = w2[i] * X[i] + w1[i] * q1 + w0[i] * q2 + bb[i];
;                     o[i] = MODE == 0 ? silu_f(cv) * Y[i] : cv * Y[i];
;                 }
;                 if (m == 0 && fr < 2) {
;                     bf16_t* hx = halo + ((size_t)strip * 6 + 2 + fr) * C + c0; bf16_t* hy = halo + ((size_t)strip * 6 + 4 + fr) * C + c0;
;                     u32x4 px, py; px.x = cvt_pk_bf16(X[0], X[1]); px.y = cvt_pk_bf16(X[2], X[3]); px.z = cvt_pk_bf16(X[4 % NV], X[5 % NV]); px.w = cvt_pk_bf16(X[6 % NV], X[7 % NV]);
;                     py.x = cvt_pk_bf16(Y[0], Y[1]); py.y = cvt_pk_bf16(Y[2], Y[3]); py.z = cvt_pk_bf16(Y[4 % NV], Y[5 % NV]); py.w = cvt_pk_bf16(Y[6 % NV], Y[7 % NV]);
;                     if (MODE == 0) { *(u32x4*)hx = px; *(u32x4*)hy = py; } else { u32x2 a; a.x = px.x; a.y = px.y; *(u32x2*)hx = a; u32x2 b; b.x = py.x; b.y = py.y; *(u32x2*)hy = b; }
;                 } else {
;                     if (MODE == 0) { u32x4 w; w.x = cvt_pk_bf16(o[0], o[1]); w.y = cvt_pk_bf16(o[2], o[3]); w.z = cvt_pk_bf16(o[4 % NV], o[5 % NV]); w.w = cvt_pk_bf16(o[6 % NV], o[7 % NV]);
	v_fma_f32 v211, v13, v137, v175
	v_fma_f32 v212, v14, v138, v176
	v_fma_f32 v213, v15, v139, v177
	v_fma_f32 v214, v8, v140, v178
	v_fma_f32 v215, v9, v141, v179
	v_fma_f32 v216, v10, v142, v180
	v_fma_f32 v217, v11, v143, v181
	v_cvt_pk_bf16_f32 v236, v12, v13
	v_cvt_pk_bf16_f32 v237, v14, v15
	v_cvt_pk_bf16_f32 v238, v8, v9
	v_cvt_pk_bf16_f32 v239, v10, v11
	v_add_u32_e32 v235, 0xffffd400, v233
	s_and_b64 exec, exec, s[10:11]
	global_store_dwordx4 v235, v[236:239], s[42:43]
	s_mov_b64 exec, s[24:25]
	v_fmac_f32_dpp v210, v12, v128 row_shr:1 row_mask:0xf bank_mask:0xf
	v_fmac_f32_dpp v211, v13, v129 row_shr:1 row_mask:0xf bank_mask:0xf
	v_fmac_f32_dpp v212, v14, v130 row_shr:1 row_mask:0xf bank_mask:0xf
	v_fmac_f32_dpp v213, v15, v131 row_shr:1 row_mask:0xf bank_mask:0xf
	v_fmac_f32_dpp v214, v8, v132 row_shr:1 row_mask:0xf bank_mask:0xf
	v_fmac_f32_dpp v215, v9, v133 row_shr:1 row_mask:0xf bank_mask:0xf
	v_fmac_f32_dpp v216, v10, v134 row_shr:1 row_mask:0xf bank_mask:0xf
	v_fmac_f32_dpp v217, v11, v135 row_shr:1 row_mask:0xf bank_mask:0xf
	v_fmac_f32_dpp v210, v12, v88 row_shr:2 row_mask:0xf bank_mask:0xf
	v_fmac_f32_dpp v211, v13, v89 row_shr:2 row_mask:0xf bank_mask:0xf
	v_fmac_f32_dpp v212, v14, v90 row_shr:2 row_mask:0xf bank_mask:0xf
	v_fmac_f32_dpp v213, v15, v91 row_shr:2 row_mask:0xf bank_mask:0xf
	v_fmac_f32_dpp v214, v8, v92 row_shr:2 row_mask:0xf bank_mask:0xf
	v_fmac_f32_dpp v215, v9, v93 row_shr:2 row_mask:0xf bank_mask:0xf
	v_fmac_f32_dpp v216, v10, v94 row_shr:2 row_mask:0xf bank_mask:0xf
	v_fmac_f32_dpp v217, v11, v95 row_shr:2 row_mask:0xf bank_mask:0xf
	v_fmac_f32_dpp v210, v28, v128 row_shl:15 row_mask:0xf bank_mask:0xf
	v_fmac_f32_dpp v211, v29, v129 row_shl:15 row_mask:0xf bank_mask:0xf
	v_fmac_f32_dpp v212, v30, v130 row_shl:15 row_mask:0xf bank_mask:0xf
	v_fmac_f32_dpp v213, v31, v131 row_shl:15 row_mask:0xf bank_mask:0xf
	v_fmac_f32_dpp v214, v24, v132 row_shl:15 row_mask:0xf bank_mask:0xf
	v_fmac_f32_dpp v215, v25, v133 row_shl:15 row_mask:0xf bank_mask:0xf
	v_fmac_f32_dpp v216, v26, v134 row_shl:15 row_mask:0xf bank_mask:0xf
	v_fmac_f32_dpp v217, v27, v135 row_shl:15 row_mask:0xf bank_mask:0xf
	v_fmac_f32_dpp v210, v28, v88 row_shl:14 row_mask:0xf bank_mask:0xf
	v_fmac_f32_dpp v211, v29, v89 row_shl:14 row_mask:0xf bank_mask:0xf
	v_fmac_f32_dpp v212, v30, v90 row_shl:14 row_mask:0xf bank_mask:0xf
	v_fmac_f32_dpp v213, v31, v91 row_shl:14 row_mask:0xf bank_mask:0xf
	v_fmac_f32_dpp v214, v24, v92 row_shl:14 row_mask:0xf bank_mask:0xf
	v_fmac_f32_dpp v215, v25, v93 row_shl:14 row_mask:0xf bank_mask:0xf
	v_fmac_f32_dpp v216, v26, v94 row_shl:14 row_mask:0xf bank_mask:0xf
	v_fmac_f32_dpp v217, v27, v95 row_shl:14 row_mask:0xf bank_mask:0xf
	v_exp_f32_e32 v218, v210
	v_exp_f32_e32 v219, v211
	v_exp_f32_e32 v220, v212
	v_exp_f32_e32 v221, v213
	v_exp_f32_e32 v222, v214
	v_exp_f32_e32 v223, v215
	v_exp_f32_e32 v224, v216
	v_exp_f32_e32 v225, v217
	v_fma_f32 v218, v218, v209, v209
	v_fma_f32 v219, v219, v209, v209
	v_fma_f32 v220, v220, v209, v209
	v_fma_f32 v221, v221, v209, v209
	v_fma_f32 v222, v222, v209, v209
	v_fma_f32 v223, v223, v209, v209
	v_fma_f32 v224, v224, v209, v209
	v_fma_f32 v225, v225, v209, v209
	v_rcp_f32_e32 v218, v218
	v_rcp_f32_e32 v219, v219
	v_rcp_f32_e32 v220, v220
	v_rcp_f32_e32 v221, v221
	v_rcp_f32_e32 v222, v222
	v_rcp_f32_e32 v223, v223
	v_rcp_f32_e32 v224, v224
	v_rcp_f32_e32 v225, v225
	v_mul_f32_e32 v210, v210, v218
	v_mul_f32_e32 v211, v211, v219
	v_mul_f32_e32 v212, v212, v220
	v_mul_f32_e32 v213, v213, v221
	v_mul_f32_e32 v214, v214, v222
	v_mul_f32_e32 v215, v215, v223
	v_mul_f32_e32 v216, v216, v224
	v_mul_f32_e32 v217, v217, v225
	v_mul_f32_e32 v4, v210, v4
	v_mul_f32_e32 v5, v211, v5
	v_mul_f32_e32 v6, v212, v6
	v_mul_f32_e32 v7, v213, v7
	v_mul_f32_e32 v0, v214, v0
	v_mul_f32_e32 v1, v215, v1
	v_mul_f32_e32 v2, v216, v2
	v_mul_f32_e32 v3, v217, v3
	v_cvt_pk_bf16_f32 v226, v4, v5
	v_cvt_pk_bf16_f32 v227, v6, v7
	v_cvt_pk_bf16_f32 v228, v0, v1
	v_cvt_pk_bf16_f32 v229, v2, v3
	v_add_u32_e32 v234, 0xf2000, v230
	global_store_dwordx4 v234, v[226:229], s[96:97] nt

;     __device__ __forceinline__ void operator()(const Acc& acc, const Unit& u, int wr, int wc, int fr, int fq, LAS unsigned char* lds, f32x4 epar) const {
;     ...
;         LAS float* pw = (LAS float*)(lds + STAGE_BYTES + 64 + (wr * 4 + wc) * 1024);
;         *(LAS f32x4*)(pw + (fq * 16 + fr) * 4) = epar;
;         asm volatile("s_waitcnt lgkmcnt(0)" ::: "memory");
;         float w0[NV], w1[NV], w2[NV], bb[NV];
; #pragma unroll
;         for (int i = 0; i < NV; i += 4) { const f32x4 a = *(const LAS f32x4*)(pw + NV * fq + i), b = *(const LAS f32x4*)(pw + 32 + NV * fq + i), c = *(const LAS f32x4*)(pw + 64 + NV * fq + i);
;             f32x4 d = (f32x4){0.f, 0.f, 0.f, 0.f}; if (MODE == 0) d = *(const LAS f32x4*)(pw + 96 + NV * fq + i);
; #pragma unroll
;             for (int j = 0; j < 4; ++j) { w0[i + j] = a[j]; w1[i + j] = b[j]; w2[i + j] = c[j]; bb[i + j] = d[j]; } }
;         float sq[2][4];
; #pragma unroll
;         for (int ai = 0; ai < 2; ++ai)
; #pragma unroll
;             for (int m = 0; m < 4; ++m) sq[ai][m] = pw[128 + ai * 64 + m * 16 + fr];
; #pragma unroll
;         for (int ai = 0; ai < 2; ++ai) {
;             const int strip = u.pm * 4 + ai * 2 + wr;
;             float p1prev[NV], p2prev[NV];
; #pragma unroll
;             for (int i = 0; i < NV; ++i) { p1prev[i] = 0.f; p2prev[i] = 0.f; }
; #pragma unroll
;             for (int m = 0; m < 4; ++m) {
;                 const int r = u.pm * BM + ai * HALF + wr * 64 + m * 16 + fr;
;                 const float rs = __builtin_amdgcn_rsqf(sq[ai][m] * (1.0f / DM) + RMS_EPS);
;                 float X[NV], Y[NV], o[NV];
;                 if (MODE == 0) {
; #pragma unroll
;                     for (int n = 0; n < 2; ++n)
; #pragma unroll
;                         for (int j = 0; j < 4; ++j) { X[n * 4 + j] = acc[ai][0][m][n][j] * rs; Y[n * 4 + j] = acc[ai][1][m][n][j] * rs; }
;                 } else {
; #pragma unroll
;                     for (int j = 0; j < 4; ++j) { X[j] = (acc[ai][0][m][1][j] * rs) * (acc[ai][1][m][0][j] * rs); Y[j] = acc[ai][0][m][0][j] * rs; }
;                 }
; #pragma unroll
;                 for (int i = 0; i < NV; ++i) {
;                     const float a1 = dpp_rot<0x121>(X[i]), a2 = dpp_rot<0x122>(X[i]);
;                     const float q1 = fr >= 1 ? a1 : p1prev[i], q2 = fr >= 2 ? a2 : p2prev[i];
;                     p1prev[i] = a1; p2prev[i] = a2;
.LBB0_986:
	ds_write_b128 v198, v[72:75]
	s_mov_b64 s[24:25], exec
	s_waitcnt lgkmcnt(0)
	ds_read_b128 v[88:91], v199
	ds_read_b128 v[92:95], v199 offset:16
	ds_read_b128 v[128:131], v199 offset:128
	ds_read_b128 v[132:135], v199 offset:144
	ds_read_b128 v[136:139], v199 offset:256
	ds_read_b128 v[140:143], v199 offset:272
	ds_read_b128 v[174:177], v199 offset:384
	ds_read_b128 v[178:181], v199 offset:400
	ds_read2_b32 v[182:183], v191 offset0:128 offset1:144
	ds_read2_b32 v[184:185], v191 offset0:160 offset1:176
	ds_read2_b32 v[76:77], v191 offset0:192 offset1:208
	ds_read2_b32 v[78:79], v191 offset0:224 offset1:240
	v_lshl_add_u32 v230, s66, 8, v190
	v_lshl_or_b32 v231, s70, 7, v192
	v_mul_u32_u24_e32 v230, 0x1600, v230
	s_lshl_b32 s26, s66, 2
	s_add_i32 s26, s26, s15
	s_mul_i32 s16, s26, 6
	v_and_b32_e32 v233, 15, v190
	v_lshl_add_u32 v230, v231, 1, v230
	v_add_u32_e32 v233, s16, v233
	v_mul_u32_u24_e32 v233, 0x1600, v233
	s_nop 0
	v_lshl_add_u32 v233, v231, 1, v233
	s_waitcnt lgkmcnt(0)
	v_mul_f32_e32 v88, 0xbfb8aa3b, v88
	v_mul_f32_e32 v89, 0xbfb8aa3b, v89
	v_mul_f32_e32 v90, 0xbfb8aa3b, v90
	v_mul_f32_e32 v91, 0xbfb8aa3b, v91
	v_mul_f32_e32 v92, 0xbfb8aa3b, v92
	v_mul_f32_e32 v93, 0xbfb8aa3b, v93
	v_mul_f32_e32 v94, 0xbfb8aa3b, v94
	v_mul_f32_e32 v95, 0xbfb8aa3b, v95
	v_mul_f32_e32 v128, 0xbfb8aa3b, v128
	v_mul_f32_e32 v129, 0xbfb8aa3b, v129
	v_mul_f32_e32 v130, 0xbfb8aa3b, v130
	v_mul_f32_e32 v131, 0xbfb8aa3b, v131
	v_mul_f32_e32 v132, 0xbfb8aa3b, v132
	v_mul_f32_e32 v133, 0xbfb8aa3b, v133
	v_mul_f32_e32 v134, 0xbfb8aa3b, v134
	v_mul_f32_e32 v135, 0xbfb8aa3b, v135
	v_mul_f32_e32 v136, 0xbfb8aa3b, v136
	v_mul_f32_e32 v137, 0xbfb8aa3b, v137
	v_mul_f32_e32 v138, 0xbfb8aa3b, v138
	v_mul_f32_e32 v139, 0xbfb8aa3b, v139
	v_mul_f32_e32 v140, 0xbfb8aa3b, v140
	v_mul_f32_e32 v141, 0xbfb8aa3b, v141
	v_mul_f32_e32 v142, 0xbfb8aa3b, v142
	v_mul_f32_e32 v143, 0xbfb8aa3b, v143
	v_mul_f32_e32 v174, 0xbfb8aa3b, v174
	v_mul_f32_e32 v175, 0xbfb8aa3b, v175
	v_mul_f32_e32 v176, 0xbfb8aa3b, v176
	v_mul_f32_e32 v177, 0xbfb8aa3b, v177
	v_mul_f32_e32 v178, 0xbfb8aa3b, v178
	v_mul_f32_e32 v179, 0xbfb8aa3b, v179
	v_mul_f32_e32 v180, 0xbfb8aa3b, v180
	v_mul_f32_e32 v181, 0xbfb8aa3b, v181
	v_fmamk_f32 v182, v182, 0x3a800000, v200
	v_fmamk_f32 v183, v183, 0x3a800000, v200
	v_fmamk_f32 v184, v184, 0x3a800000, v200
	v_fmamk_f32 v185, v185, 0x3a800000, v200
	v_fmamk_f32 v76, v76, 0x3a800000, v200
	v_fmamk_f32 v77, v77, 0x3a800000, v200
	v_fmamk_f32 v78, v78, 0x3a800000, v200
	v_fmamk_f32 v79, v79, 0x3a800000, v200
	v_mul_f32_e32 v202, 0xbfb8aa3b, v182
	v_mul_f32_e32 v203, 0xbfb8aa3b, v183
	v_mul_f32_e32 v204, 0xbfb8aa3b, v184
	v_mul_f32_e32 v205, 0xbfb8aa3b, v185
	v_mul_f32_e32 v206, 0xbfb8aa3b, v76
	v_mul_f32_e32 v207, 0xbfb8aa3b, v77
	v_mul_f32_e32 v208, 0xbfb8aa3b, v78
	v_mul_f32_e32 v209, 0xbfb8aa3b, v79
	v_rsq_f32_e32 v182, v182
	v_rsq_f32_e32 v183, v183
	v_rsq_f32_e32 v184, v184
	v_rsq_f32_e32 v185, v185
	v_rsq_f32_e32 v76, v76
	v_rsq_f32_e32 v77, v77
	v_rsq_f32_e32 v78, v78
	v_rsq_f32_e32 v79, v79
	s_nop 0
	v_mul_f32_e32 v202, v202, v182
	v_mul_f32_e32 v203, v203, v183
	v_mul_f32_e32 v204, v204, v184
	v_mul_f32_e32 v205, v205, v185
	v_mul_f32_e32 v206, v206, v76
	v_mul_f32_e32 v207, v207, v77
	v_mul_f32_e32 v208, v208, v78
	v_mul_f32_e32 v209, v209, v79
	v_mul_f32_e32 v152, v152, v182
	v_mul_f32_e32 v153, v153, v182
	v_mul_f32_e32 v154, v154, v182
	v_mul_f32_e32 v155, v155, v182
	v_mul_f32_e32 v144, v144, v182
	v_mul_f32_e32 v145, v145, v182
	v_mul_f32_e32 v146, v146, v182
	v_mul_f32_e32 v147, v147, v182
	v_fma_f32 v210, v152, v136, v174
	v_fma_f32 v211, v153, v137, v175
	v_fma_f32 v212, v154, v138, v176
	v_fma_f32 v213, v155, v139, v177
	v_fma_f32 v214, v144, v140, v178
	v_fma_f32 v215, v145, v141, v179
	v_fma_f32 v216, v146, v142, v180
	v_fma_f32 v217, v147, v143, v181
	v_mul_f32_e32 v218, v156, v182
	v_mul_f32_e32 v219, v157, v182
	v_mul_f32_e32 v220, v158, v182
	v_mul_f32_e32 v221, v159, v182
	v_mul_f32_e32 v222, v148, v182
	v_mul_f32_e32 v223, v149, v182
	v_mul_f32_e32 v224, v150, v182
	v_mul_f32_e32 v225, v151, v182
	v_cvt_pk_bf16_f32 v236, v152, v153
	v_cvt_pk_bf16_f32 v237, v154, v155
	v_cvt_pk_bf16_f32 v238, v144, v145
	v_cvt_pk_bf16_f32 v239, v146, v147
	v_cvt_pk_bf16_f32 v240, v218, v219
	v_cvt_pk_bf16_f32 v241, v220, v221
	v_cvt_pk_bf16_f32 v242, v222, v223
	v_cvt_pk_bf16_f32 v243, v224, v225
	v_add_u32_e32 v234, 0x2c00, v233
	v_add_u32_e32 v235, 0x5800, v233
	s_andn2_b64 exec, exec, s[8:9]
	global_store_dwordx4 v234, v[236:239], s[42:43]
	global_store_dwordx4 v235, v[240:243], s[42:43]
	s_mov_b64 exec, s[24:25]
	v_fmac_f32_dpp v210, v152, v128 row_shr:1 row_mask:0xf bank_mask:0xf
	v_fmac_f32_dpp v211, v153, v129 row_shr:1 row_mask:0xf bank_mask:0xf
	v_fmac_f32_dpp v212, v154, v130 row_shr:1 row_mask:0xf bank_mask:0xf
	v_fmac_f32_dpp v213, v155, v131 row_shr:1 row_mask:0xf bank_mask:0xf
	v_fmac_f32_dpp v214, v144, v132 row_shr:1 row_mask:0xf bank_mask:0xf
	v_fmac_f32_dpp v215, v145, v133 row_shr:1 row_mask:0xf bank_mask:0xf
	v_fmac_f32_dpp v216, v146, v134 row_shr:1 row_mask:0xf bank_mask:0xf
	v_fmac_f32_dpp v217, v147, v135 row_shr:1 row_mask:0xf bank_mask:0xf
	v_fmac_f32_dpp v210, v152, v88 row_shr:2 row_mask:0xf bank_mask:0xf
	v_fmac_f32_dpp v211, v153, v89 row_shr:2 row_mask:0xf bank_mask:0xf
	v_fmac_f32_dpp v212, v154, v90 row_shr:2 row_mask:0xf bank_mask:0xf
	v_fmac_f32_dpp v213, v155, v91 row_shr:2 row_mask:0xf bank_mask:0xf
	v_fmac_f32_dpp v214, v144, v92 row_shr:2 row_mask:0xf bank_mask:0xf
	v_fmac_f32_dpp v215, v145, v93 row_shr:2 row_mask:0xf bank_mask:0xf
	v_fmac_f32_dpp v216, v146, v94 row_shr:2 row_mask:0xf bank_mask:0xf
; __device__ __forceinline__ unsigned cvt_pk_bf16(float lo, float hi) { unsigned r; asm volatile("v_cvt_pk_bf16_f32 %0, %1, %2" : "=v"(r) : "v"(lo), "v"(hi)); return r; }
; __device__ __forceinline__ float silu_f(float x) { return x * __builtin_amdgcn_rcpf(1.0f + __builtin_amdgcn_exp2f(x * -1.44269504f)); }
; template <int CTRL> __device__ __forceinline__ float dpp_rot(float x) { return __int_as_float(__builtin_amdgcn_mov_dpp(__float_as_int(x), CTRL, 0xf, 0xf, false)); }
;     __device__ __forceinline__ void operator()(const Acc& acc, const Unit& u, int wr, int wc, int fr, int fq, LAS unsigned char* lds, f32x4 epar) const {
;     ...
; #pragma unroll
;                 for (int i = 0; i < NV; ++i) {
;                     const float a1 = dpp_rot<0x121>(X[i]), a2 = dpp_rot<0x122>(X[i]);
;                     const float q1 = fr >= 1 ? a1 : p1prev[i], q2 = fr >= 2 ? a2 : p2prev[i];
;                     p1prev[i] = a1; p2prev[i] = a2;
;                     const float cv = w2[i] * X[i] + w1[i] * q1 + w0[i] * q2 + bb[i];
;                     o[i] = MODE == 0 ? silu_f(cv) * Y[i] : cv * Y[i];
;                 }
;                 if (m == 0 && fr < 2) {
;                     bf16_t* hx = halo + ((size_t)strip * 6 + 2 + fr) * C + c0; bf16_t* hy = halo + ((size_t)strip * 6 + 4 + fr) * C + c0;
;                     u32x4 px, py; px.x = cvt_pk_bf16(X[0], X[1]); px.y = cvt_pk_bf16(X[2], X[3]); px.z = cvt_pk_bf16(X[4 % NV], X[5 % NV]); px.w = cvt_pk_bf16(X[6 % NV], X[7 % NV]);
;                     py.x = cvt_pk_bf16(Y[0], Y[1]); py.y = cvt_pk_bf16(Y[2], Y[3]); py.z = cvt_pk_bf16(Y[4 % NV], Y[5 % NV]); py.w = cvt_pk_bf16(Y[6 % NV], Y[7 % NV]);
;                     if (MODE == 0) { *(u32x4*)hx = px; *(u32x4*)hy = py; } else { u32x2 a; a.x = px.x; a.y = px.y; *(u32x2*)hx = a; u32x2 b; b.x = py.x; b.y = py.y; *(u32x2*)hy = b; }
;                 } else {
;                     if (MODE == 0) { u32x4 w; w.x = cvt_pk_bf16(o[0], o[1]); w.y = cvt_pk_bf16(o[2], o[3]); w.z = cvt_pk_bf16(o[4 % NV], o[5 % NV]); w.w = cvt_pk_bf16(o[6 % NV], o[7 % NV]);
;                         __builtin_nontemporal_store(w, (u32x4*)(out + (size_t)r * C + c0)); }
	v_fmac_f32_dpp v217, v147, v95 row_shr:2 row_mask:0xf bank_mask:0xf
	v_exp_f32_e32 v218, v210
	v_exp_f32_e32 v219, v211
	v_exp_f32_e32 v220, v212
	v_exp_f32_e32 v221, v213
	v_exp_f32_e32 v222, v214
	v_exp_f32_e32 v223, v215
	v_exp_f32_e32 v224, v216
	v_exp_f32_e32 v225, v217
	v_fma_f32 v218, v218, v202, v202
	v_fma_f32 v219, v219, v202, v202
	v_fma_f32 v220, v220, v202, v202
	v_fma_f32 v221, v221, v202, v202
	v_fma_f32 v222, v222, v202, v202
	v_fma_f32 v223, v223, v202, v202
	v_fma_f32 v224, v224, v202, v202
	v_fma_f32 v225, v225, v202, v202
	v_rcp_f32_e32 v218, v218
	v_rcp_f32_e32 v219, v219
	v_rcp_f32_e32 v220, v220
	v_rcp_f32_e32 v221, v221
	v_rcp_f32_e32 v222, v222
	v_rcp_f32_e32 v223, v223
	v_rcp_f32_e32 v224, v224
	v_rcp_f32_e32 v225, v225
	v_mul_f32_e32 v210, v210, v218
	v_mul_f32_e32 v211, v211, v219
	v_mul_f32_e32 v212, v212, v220
	v_mul_f32_e32 v213, v213, v221
	v_mul_f32_e32 v214, v214, v222
	v_mul_f32_e32 v215, v215, v223
	v_mul_f32_e32 v216, v216, v224
	v_mul_f32_e32 v217, v217, v225
	v_mul_f32_e32 v156, v210, v156
	v_mul_f32_e32 v157, v211, v157
	v_mul_f32_e32 v158, v212, v158
	v_mul_f32_e32 v159, v213, v159
	v_mul_f32_e32 v148, v214, v148
	v_mul_f32_e32 v149, v215, v149
	v_mul_f32_e32 v150, v216, v150
	v_mul_f32_e32 v151, v217, v151
	v_cvt_pk_bf16_f32 v226, v156, v157
	v_cvt_pk_bf16_f32 v227, v158, v159
	v_cvt_pk_bf16_f32 v228, v148, v149
	v_cvt_pk_bf16_f32 v229, v150, v151
	v_add_u32_e32 v234, 0x0, v230
	s_and_b64 exec, exec, s[8:9]
	global_store_dwordx4 v234, v[226:229], s[96:97] nt
	s_mov_b64 exec, s[24:25]
	v_mul_f32_e32 v124, v124, v183
	v_mul_f32_e32 v125, v125, v183
	v_mul_f32_e32 v126, v126, v183
	v_mul_f32_e32 v127, v127, v183
	v_mul_f32_e32 v120, v120, v183
	v_mul_f32_e32 v121, v121, v183
	v_mul_f32_e32 v122, v122, v183
	v_mul_f32_e32 v123, v123, v183
	v_fma_f32 v210, v124, v136, v174
	v_fma_f32 v211, v125, v137, v175
	v_fma_f32 v212, v126, v138, v176
	v_fma_f32 v213, v127, v139, v177
	v_fma_f32 v214, v120, v140, v178
	v_fma_f32 v215, v121, v141, v179
	v_fma_f32 v216, v122, v142, v180
	v_fma_f32 v217, v123, v143, v181
	v_fmac_f32_dpp v210, v124, v128 row_shr:1 row_mask:0xf bank_mask:0xf
	v_fmac_f32_dpp v211, v125, v129 row_shr:1 row_mask:0xf bank_mask:0xf
	v_fmac_f32_dpp v212, v126, v130 row_shr:1 row_mask:0xf bank_mask:0xf
	v_fmac_f32_dpp v213, v127, v131 row_shr:1 row_mask:0xf bank_mask:0xf
	v_fmac_f32_dpp v214, v120, v132 row_shr:1 row_mask:0xf bank_mask:0xf
	v_fmac_f32_dpp v215, v121, v133 row_shr:1 row_mask:0xf bank_mask:0xf
	v_fmac_f32_dpp v216, v122, v134 row_shr:1 row_mask:0xf bank_mask:0xf
	v_fmac_f32_dpp v217, v123, v135 row_shr:1 row_mask:0xf bank_mask:0xf
	v_fmac_f32_dpp v210, v124, v88 row_shr:2 row_mask:0xf bank_mask:0xf
	v_fmac_f32_dpp v211, v125, v89 row_shr:2 row_mask:0xf bank_mask:0xf
	v_fmac_f32_dpp v212, v126, v90 row_shr:2 row_mask:0xf bank_mask:0xf
	v_fmac_f32_dpp v213, v127, v91 row_shr:2 row_mask:0xf bank_mask:0xf
	v_fmac_f32_dpp v214, v120, v92 row_shr:2 row_mask:0xf bank_mask:0xf
	v_fmac_f32_dpp v215, v121, v93 row_shr:2 row_mask:0xf bank_mask:0xf
	v_fmac_f32_dpp v216, v122, v94 row_shr:2 row_mask:0xf bank_mask:0xf
	v_fmac_f32_dpp v217, v123, v95 row_shr:2 row_mask:0xf bank_mask:0xf
	v_fmac_f32_dpp v210, v152, v128 row_shl:15 row_mask:0xf bank_mask:0xf
	v_fmac_f32_dpp v211, v153, v129 row_shl:15 row_mask:0xf bank_mask:0xf
	v_fmac_f32_dpp v212, v154, v130 row_shl:15 row_mask:0xf bank_mask:0xf
	v_fmac_f32_dpp v213, v155, v131 row_shl:15 row_mask:0xf bank_mask:0xf
	v_fmac_f32_dpp v214, v144, v132 row_shl:15 row_mask:0xf bank_mask:0xf
	v_fmac_f32_dpp v215, v145, v133 row_shl:15 row_mask:0xf bank_mask:0xf
	v_fmac_f32_dpp v216, v146, v134 row_shl:15 row_mask:0xf bank_mask:0xf
	v_fmac_f32_dpp v217, v147, v135 row_shl:15 row_mask:0xf bank_mask:0xf
	v_fmac_f32_dpp v210, v152, v88 row_shl:14 row_mask:0xf bank_mask:0xf
	v_fmac_f32_dpp v211, v153, v89 row_shl:14 row_mask:0xf bank_mask:0xf
	v_fmac_f32_dpp v212, v154, v90 row_shl:14 row_mask:0xf bank_mask:0xf
	v_fmac_f32_dpp v213, v155, v91 row_shl:14 row_mask:0xf bank_mask:0xf
	v_fmac_f32_dpp v214, v144, v92 row_shl:14 row_mask:0xf bank_mask:0xf
	v_fmac_f32_dpp v215, v145, v93 row_shl:14 row_mask:0xf bank_mask:0xf
	v_fmac_f32_dpp v216, v146, v94 row_shl:14 row_mask:0xf bank_mask:0xf
	v_fmac_f32_dpp v217, v147, v95 row_shl:14 row_mask:0xf bank_mask:0xf
	v_exp_f32_e32 v218, v210
	v_exp_f32_e32 v219, v211
	v_exp_f32_e32 v220, v212
	v_exp_f32_e32 v221, v213
	v_exp_f32_e32 v222, v214
	v_exp_f32_e32 v223, v215
	v_exp_f32_e32 v224, v216
	v_exp_f32_e32 v225, v217
	v_fma_f32 v218, v218, v203, v203
	v_fma_f32 v219, v219, v203, v203
	v_fma_f32 v220, v220, v203, v203
	v_fma_f32 v221, v221, v203, v203
	v_fma_f32 v222, v222, v203, v203
	v_fma_f32 v223, v223, v203, v203
	v_fma_f32 v224, v224, v203, v203
	v_fma_f32 v225, v225, v203, v203
	v_rcp_f32_e32 v218, v218
	v_rcp_f32_e32 v219, v219
	v_rcp_f32_e32 v220, v220
	v_rcp_f32_e32 v221, v221
	v_rcp_f32_e32 v222, v222
	v_rcp_f32_e32 v223, v223
	v_rcp_f32_e32 v224, v224
	v_rcp_f32_e32 v225, v225
	v_mul_f32_e32 v210, v210, v218
	v_mul_f32_e32 v211, v211, v219
	v_mul_f32_e32 v212, v212, v220
	v_mul_f32_e32 v213, v213, v221
	v_mul_f32_e32 v214, v214, v222
	v_mul_f32_e32 v215, v215, v223
	v_mul_f32_e32 v216, v216, v224
	v_mul_f32_e32 v217, v217, v225
	v_mul_f32_e32 v116, v210, v116
	v_mul_f32_e32 v117, v211, v117
	v_mul_f32_e32 v118, v212, v118
	v_mul_f32_e32 v119, v213, v119
	v_mul_f32_e32 v112, v214, v112
	v_mul_f32_e32 v113, v215, v113
	v_mul_f32_e32 v114, v216, v114
	v_mul_f32_e32 v115, v217, v115
	v_cvt_pk_bf16_f32 v226, v116, v117
	v_cvt_pk_bf16_f32 v227, v118, v119
	v_cvt_pk_bf16_f32 v228, v112, v113
;     __device__ __forceinline__ void operator()(const Acc& acc, const Unit& u, int wr, int wc, int fr, int fq, LAS unsigned char* lds, f32x4 epar) const {
;     ...
;                 const float rs = __builtin_amdgcn_rsqf(sq[ai][m] * (1.0f / DM) + RMS_EPS);
;                 float X[NV], Y[NV], o[NV];
;                 if (MODE == 0) {
; #pragma unroll
;                     for (int n = 0; n < 2; ++n)
; #pragma unroll
;                         for (int j = 0; j < 4; ++j) { X[n * 4 + j] = acc[ai][0][m][n][j] * rs; Y[n * 4 + j] = acc[ai][1][m][n][j] * rs; }
;                 } else {
; #pragma unroll
;                     for (int j = 0; j < 4; ++j) { X[j] = (acc[ai][0][m][1][j] * rs) * (acc[ai][1][m][0][j] * rs); Y[j] = acc[ai][0][m][0][j] * rs; }
;                 }
; #pragma unroll
;                 for (int i = 0; i < NV; ++i) {
;                     const float a1 = dpp_rot<0x121>(X[i]), a2 = dpp_rot<0x122>(X[i]);
;                     const float q1 = fr >= 1 ? a1 : p1prev[i], q2 = fr >= 2 ? a2 : p2prev[i];
;                     p1prev[i] = a1; p2prev[i] = a2;
;                     const float cv = w2[i] * X[i] + w1[i] * q1 + w0[i] * q2 + bb[i];
;                     o[i] = MODE == 0 ? silu_f(cv) * Y[i] : cv * Y[i];
;                 }
;                 if (m == 0 && fr < 2) {
;                     bf16_t* hx = halo + ((size_t)strip * 6 + 2 + fr) * C + c0; bf16_t* hy = halo + ((size_t)strip * 6 + 4 + fr) * C + c0;
;                     u32x4 px, py; px.x = cvt_pk_bf16(X[0], X[1]); px.y = cvt_pk_bf16(X[2], X[3]); px.z = cvt_pk_bf16(X[4 % NV], X[5 % NV]); px.w = cvt_pk_bf16(X[6 % NV], X[7 % NV]);
;                     py.x = cvt_pk_bf16(Y[0], Y[1]); py.y = cvt_pk_bf16(Y[2], Y[3]); py.z = cvt_pk_bf16(Y[4 % NV], Y[5 % NV]); py.w = cvt_pk_bf16(Y[6 % NV], Y[7 % NV]);
;                     if (MODE == 0) { *(u32x4*)hx = px; *(u32x4*)hy = py; } else { u32x2 a; a.x = px.x; a.y = px.y; *(u32x2*)hx = a; u32x2 b; b.x = py.x; b.y = py.y; *(u32x2*)hy = b; }
;                 } else {
;                     if (MODE == 0) { u32x4 w; w.x = cvt_pk_bf16(o[0], o[1]); w.y = cvt_pk_bf16(o[2], o[3]); w.z = cvt_pk_bf16(o[4 % NV], o[5 % NV]); w.w = cvt_pk_bf16(o[6 % NV], o[7 % NV]);
;                         __builtin_nontemporal_store(w, (u32x4*)(out + (size_t)r * C + c0)); }
	v_cvt_pk_bf16_f32 v229, v114, v115
	v_add_u32_e32 v234, 0x16000, v230
	global_store_dwordx4 v234, v[226:229], s[96:97] nt
	v_mul_f32_e32 v108, v108, v184
	v_mul_f32_e32 v109, v109, v184
	v_mul_f32_e32 v110, v110, v184
	v_mul_f32_e32 v111, v111, v184
	v_mul_f32_e32 v104, v104, v184
	v_mul_f32_e32 v105, v105, v184
	v_mul_f32_e32 v106, v106, v184
	v_mul_f32_e32 v107, v107, v184
	v_fma_f32 v210, v108, v136, v174
	v_fma_f32 v211, v109, v137, v175
	v_fma_f32 v212, v110, v138, v176
	v_fma_f32 v213, v111, v139, v177
	v_fma_f32 v214, v104, v140, v178
	v_fma_f32 v215, v105, v141, v179
	v_fma_f32 v216, v106, v142, v180
	v_fma_f32 v217, v107, v143, v181
	v_fmac_f32_dpp v210, v108, v128 row_shr:1 row_mask:0xf bank_mask:0xf
	v_fmac_f32_dpp v211, v109, v129 row_shr:1 row_mask:0xf bank_mask:0xf
	v_fmac_f32_dpp v212, v110, v130 row_shr:1 row_mask:0xf bank_mask:0xf
	v_fmac_f32_dpp v213, v111, v131 row_shr:1 row_mask:0xf bank_mask:0xf
	v_fmac_f32_dpp v214, v104, v132 row_shr:1 row_mask:0xf bank_mask:0xf
	v_fmac_f32_dpp v215, v105, v133 row_shr:1 row_mask:0xf bank_mask:0xf
	v_fmac_f32_dpp v216, v106, v134 row_shr:1 row_mask:0xf bank_mask:0xf
	v_fmac_f32_dpp v217, v107, v135 row_shr:1 row_mask:0xf bank_mask:0xf
	v_fmac_f32_dpp v210, v108, v88 row_shr:2 row_mask:0xf bank_mask:0xf
	v_fmac_f32_dpp v211, v109, v89 row_shr:2 row_mask:0xf bank_mask:0xf
	v_fmac_f32_dpp v212, v110, v90 row_shr:2 row_mask:0xf bank_mask:0xf
	v_fmac_f32_dpp v213, v111, v91 row_shr:2 row_mask:0xf bank_mask:0xf
	v_fmac_f32_dpp v214, v104, v92 row_shr:2 row_mask:0xf bank_mask:0xf
	v_fmac_f32_dpp v215, v105, v93 row_shr:2 row_mask:0xf bank_mask:0xf
	v_fmac_f32_dpp v216, v106, v94 row_shr:2 row_mask:0xf bank_mask:0xf
	v_fmac_f32_dpp v217, v107, v95 row_shr:2 row_mask:0xf bank_mask:0xf
	v_fmac_f32_dpp v210, v124, v128 row_shl:15 row_mask:0xf bank_mask:0xf
	v_fmac_f32_dpp v211, v125, v129 row_shl:15 row_mask:0xf bank_mask:0xf
	v_fmac_f32_dpp v212, v126, v130 row_shl:15 row_mask:0xf bank_mask:0xf
	v_fmac_f32_dpp v213, v127, v131 row_shl:15 row_mask:0xf bank_mask:0xf
	v_fmac_f32_dpp v214, v120, v132 row_shl:15 row_mask:0xf bank_mask:0xf
	v_fmac_f32_dpp v215, v121, v133 row_shl:15 row_mask:0xf bank_mask:0xf
	v_fmac_f32_dpp v216, v122, v134 row_shl:15 row_mask:0xf bank_mask:0xf
	v_fmac_f32_dpp v217, v123, v135 row_shl:15 row_mask:0xf bank_mask:0xf
	v_fmac_f32_dpp v210, v124, v88 row_shl:14 row_mask:0xf bank_mask:0xf
	v_fmac_f32_dpp v211, v125, v89 row_shl:14 row_mask:0xf bank_mask:0xf
	v_fmac_f32_dpp v212, v126, v90 row_shl:14 row_mask:0xf bank_mask:0xf
	v_fmac_f32_dpp v213, v127, v91 row_shl:14 row_mask:0xf bank_mask:0xf
	v_fmac_f32_dpp v214, v120, v92 row_shl:14 row_mask:0xf bank_mask:0xf
	v_fmac_f32_dpp v215, v121, v93 row_shl:14 row_mask:0xf bank_mask:0xf
	v_fmac_f32_dpp v216, v122, v94 row_shl:14 row_mask:0xf bank_mask:0xf
	v_fmac_f32_dpp v217, v123, v95 row_shl:14 row_mask:0xf bank_mask:0xf
	v_exp_f32_e32 v218, v210
	v_exp_f32_e32 v219, v211
	v_exp_f32_e32 v220, v212
	v_exp_f32_e32 v221, v213
	v_exp_f32_e32 v222, v214
	v_exp_f32_e32 v223, v215
	v_exp_f32_e32 v224, v216
	v_exp_f32_e32 v225, v217
	v_fma_f32 v218, v218, v204, v204
	v_fma_f32 v219, v219, v204, v204
	v_fma_f32 v220, v220, v204, v204
	v_fma_f32 v221, v221, v204, v204
	v_fma_f32 v222, v222, v204, v204
	v_fma_f32 v223, v223, v204, v204
	v_fma_f32 v224, v224, v204, v204
	v_fma_f32 v225, v225, v204, v204
	v_rcp_f32_e32 v218, v218
	v_rcp_f32_e32 v219, v219
	v_rcp_f32_e32 v220, v220
	v_rcp_f32_e32 v221, v221
	v_rcp_f32_e32 v222, v222
	v_rcp_f32_e32 v223, v223
	v_rcp_f32_e32 v224, v224
	v_rcp_f32_e32 v225, v225
	v_mul_f32_e32 v210, v210, v218
	v_mul_f32_e32 v211, v211, v219
	v_mul_f32_e32 v212, v212, v220
	v_mul_f32_e32 v213, v213, v221
	v_mul_f32_e32 v214, v214, v222
	v_mul_f32_e32 v215, v215, v223
	v_mul_f32_e32 v216, v216, v224
	v_mul_f32_e32 v217, v217, v225
	v_mul_f32_e32 v100, v210, v100
	v_mul_f32_e32 v101, v211, v101
	v_mul_f32_e32 v102, v212, v102
	v_mul_f32_e32 v103, v213, v103
	v_mul_f32_e32 v96, v214, v96
	v_mul_f32_e32 v97, v215, v97
	v_mul_f32_e32 v98, v216, v98
	v_mul_f32_e32 v99, v217, v99
	v_cvt_pk_bf16_f32 v226, v100, v101
	v_cvt_pk_bf16_f32 v227, v102, v103
	v_cvt_pk_bf16_f32 v228, v96, v97
	v_cvt_pk_bf16_f32 v229, v98, v99
	v_add_u32_e32 v234, 0x2c000, v230
	global_store_dwordx4 v234, v[226:229], s[96:97] nt
	v_mul_f32_e32 v84, v84, v185
	v_mul_f32_e32 v85, v85, v185
	v_mul_f32_e32 v86, v86, v185
	v_mul_f32_e32 v87, v87, v185
	v_mul_f32_e32 v80, v80, v185
	v_mul_f32_e32 v81, v81, v185
	v_mul_f32_e32 v82, v82, v185
	v_mul_f32_e32 v83, v83, v185
	v_fma_f32 v210, v84, v136, v174
	v_fma_f32 v211, v85, v137, v175
	v_fma_f32 v212, v86, v138, v176
	v_fma_f32 v213, v87, v139, v177
	v_fma_f32 v214, v80, v140, v178
	v_fma_f32 v215, v81, v141, v179
	v_fma_f32 v216, v82, v142, v180
	v_fma_f32 v217, v83, v143, v181
	v_cvt_pk_bf16_f32 v236, v84, v85
	v_cvt_pk_bf16_f32 v237, v86, v87
	v_cvt_pk_bf16_f32 v238, v80, v81
	v_cvt_pk_bf16_f32 v239, v82, v83
	v_add_u32_e32 v235, 0xfffecc00, v233
	s_and_b64 exec, exec, s[10:11]
	global_store_dwordx4 v235, v[236:239], s[42:43]
	s_mov_b64 exec, s[24:25]
	v_fmac_f32_dpp v210, v84, v128 row_shr:1 row_mask:0xf bank_mask:0xf
	v_fmac_f32_dpp v211, v85, v129 row_shr:1 row_mask:0xf bank_mask:0xf
	v_fmac_f32_dpp v212, v86, v130 row_shr:1 row_mask:0xf bank_mask:0xf
	v_fmac_f32_dpp v213, v87, v131 row_shr:1 row_mask:0xf bank_mask:0xf
	v_fmac_f32_dpp v214, v80, v132 row_shr:1 row_mask:0xf bank_mask:0xf
	v_fmac_f32_dpp v215, v81, v133 row_shr:1 row_mask:0xf bank_mask:0xf
	v_fmac_f32_dpp v216, v82, v134 row_shr:1 row_mask:0xf bank_mask:0xf
	v_fmac_f32_dpp v217, v83, v135 row_shr:1 row_mask:0xf bank_mask:0xf
;     __device__ __forceinline__ void operator()(const Acc& acc, const Unit& u, int wr, int wc, int fr, int fq, LAS unsigned char* lds, f32x4 epar) const {
;     ...
;                 const float rs = __builtin_amdgcn_rsqf(sq[ai][m] * (1.0f / DM) + RMS_EPS);
;                 float X[NV], Y[NV], o[NV];
;                 if (MODE == 0) {
; #pragma unroll
;                     for (int n = 0; n < 2; ++n)
; #pragma unroll
;                         for (int j = 0; j < 4; ++j) { X[n * 4 + j] = acc[ai][0][m][n][j] * rs; Y[n * 4 + j] = acc[ai][1][m][n][j] * rs; }
;                 } else {
; #pragma unroll
;                     for (int j = 0; j < 4; ++j) { X[j] = (acc[ai][0][m][1][j] * rs) * (acc[ai][1][m][0][j] * rs); Y[j] = acc[ai][0][m][0][j] * rs; }
;                 }
; #pragma unroll
;                 for (int i = 0; i < NV; ++i) {
;                     const float a1 = dpp_rot<0x121>(X[i]), a2 = dpp_rot<0x122>(X[i]);
;                     const float q1 = fr >= 1 ? a1 : p1prev[i], q2 = fr >= 2 ? a2 : p2prev[i];
;                     p1prev[i] = a1; p2prev[i] = a2;
;                     const float cv = w2[i] * X[i] + w1[i] * q1 + w0[i] * q2 + bb[i];
;                     o[i] = MODE == 0 ? silu_f(cv) * Y[i] : cv * Y[i];
;                 }
;                 if (m == 0 && fr < 2) {
;                     bf16_t* hx = halo + ((size_t)strip * 6 + 2 + fr) * C + c0; bf16_t* hy = halo + ((size_t)strip * 6 + 4 + fr) * C + c0;
;                     u32x4 px, py; px.x = cvt_pk_bf16(X[0], X[1]); px.y = cvt_pk_bf16(X[2], X[3]); px.z = cvt_pk_bf16(X[4 % NV], X[5 % NV]); px.w = cvt_pk_bf16(X[6 % NV], X[7 % NV]);
;                     py.x = cvt_pk_bf16(Y[0], Y[1]); py.y = cvt_pk_bf16(Y[2], Y[3]); py.z = cvt_pk_bf16(Y[4 % NV], Y[5 % NV]); py.w = cvt_pk_bf16(Y[6 % NV], Y[7 % NV]);
;                     if (MODE == 0) { *(u32x4*)hx = px; *(u32x4*)hy = py; } else { u32x2 a; a.x = px.x; a.y = px.y; *(u32x2*)hx = a; u32x2 b; b.x = py.x; b.y = py.y; *(u32x2*)hy = b; }
;                 } else {
;                     if (MODE == 0) { u32x4 w; w.x = cvt_pk_bf16(o[0], o[1]); w.y = cvt_pk_bf16(o[2], o[3]); w.z = cvt_pk_bf16(o[4 % NV], o[5 % NV]); w.w = cvt_pk_bf16(o[6 % NV], o[7 % NV]);
;                         __builtin_nontemporal_store(w, (u32x4*)(out + (size_t)r * C + c0)); }
	v_fmac_f32_dpp v210, v84, v88 row_shr:2 row_mask:0xf bank_mask:0xf
	v_fmac_f32_dpp v211, v85, v89 row_shr:2 row_mask:0xf bank_mask:0xf
	v_fmac_f32_dpp v212, v86, v90 row_shr:2 row_mask:0xf bank_mask:0xf
	v_fmac_f32_dpp v213, v87, v91 row_shr:2 row_mask:0xf bank_mask:0xf
	v_fmac_f32_dpp v214, v80, v92 row_shr:2 row_mask:0xf bank_mask:0xf
	v_fmac_f32_dpp v215, v81, v93 row_shr:2 row_mask:0xf bank_mask:0xf
	v_fmac_f32_dpp v216, v82, v94 row_shr:2 row_mask:0xf bank_mask:0xf
	v_fmac_f32_dpp v217, v83, v95 row_shr:2 row_mask:0xf bank_mask:0xf
	v_fmac_f32_dpp v210, v108, v128 row_shl:15 row_mask:0xf bank_mask:0xf
	v_fmac_f32_dpp v211, v109, v129 row_shl:15 row_mask:0xf bank_mask:0xf
	v_fmac_f32_dpp v212, v110, v130 row_shl:15 row_mask:0xf bank_mask:0xf
	v_fmac_f32_dpp v213, v111, v131 row_shl:15 row_mask:0xf bank_mask:0xf
	v_fmac_f32_dpp v214, v104, v132 row_shl:15 row_mask:0xf bank_mask:0xf
	v_fmac_f32_dpp v215, v105, v133 row_shl:15 row_mask:0xf bank_mask:0xf
	v_fmac_f32_dpp v216, v106, v134 row_shl:15 row_mask:0xf bank_mask:0xf
	v_fmac_f32_dpp v217, v107, v135 row_shl:15 row_mask:0xf bank_mask:0xf
	v_fmac_f32_dpp v210, v108, v88 row_shl:14 row_mask:0xf bank_mask:0xf
	v_fmac_f32_dpp v211, v109, v89 row_shl:14 row_mask:0xf bank_mask:0xf
	v_fmac_f32_dpp v212, v110, v90 row_shl:14 row_mask:0xf bank_mask:0xf
	v_fmac_f32_dpp v213, v111, v91 row_shl:14 row_mask:0xf bank_mask:0xf
	v_fmac_f32_dpp v214, v104, v92 row_shl:14 row_mask:0xf bank_mask:0xf
	v_fmac_f32_dpp v215, v105, v93 row_shl:14 row_mask:0xf bank_mask:0xf
	v_fmac_f32_dpp v216, v106, v94 row_shl:14 row_mask:0xf bank_mask:0xf
	v_fmac_f32_dpp v217, v107, v95 row_shl:14 row_mask:0xf bank_mask:0xf
	v_exp_f32_e32 v218, v210
	v_exp_f32_e32 v219, v211
	v_exp_f32_e32 v220, v212
	v_exp_f32_e32 v221, v213
	v_exp_f32_e32 v222, v214
	v_exp_f32_e32 v223, v215
	v_exp_f32_e32 v224, v216
	v_exp_f32_e32 v225, v217
	v_fma_f32 v218, v218, v205, v205
	v_fma_f32 v219, v219, v205, v205
	v_fma_f32 v220, v220, v205, v205
	v_fma_f32 v221, v221, v205, v205
	v_fma_f32 v222, v222, v205, v205
	v_fma_f32 v223, v223, v205, v205
	v_fma_f32 v224, v224, v205, v205
	v_fma_f32 v225, v225, v205, v205
	v_rcp_f32_e32 v218, v218
	v_rcp_f32_e32 v219, v219
	v_rcp_f32_e32 v220, v220
	v_rcp_f32_e32 v221, v221
	v_rcp_f32_e32 v222, v222
	v_rcp_f32_e32 v223, v223
	v_rcp_f32_e32 v224, v224
	v_rcp_f32_e32 v225, v225
	v_mul_f32_e32 v210, v210, v218
	v_mul_f32_e32 v211, v211, v219
	v_mul_f32_e32 v212, v212, v220
	v_mul_f32_e32 v213, v213, v221
	v_mul_f32_e32 v214, v214, v222
	v_mul_f32_e32 v215, v215, v223
	v_mul_f32_e32 v216, v216, v224
	v_mul_f32_e32 v217, v217, v225
	v_mul_f32_e32 v68, v210, v68
	v_mul_f32_e32 v69, v211, v69
	v_mul_f32_e32 v70, v212, v70
	v_mul_f32_e32 v71, v213, v71
	v_mul_f32_e32 v64, v214, v64
	v_mul_f32_e32 v65, v215, v65
	v_mul_f32_e32 v66, v216, v66
	v_mul_f32_e32 v67, v217, v67
	v_cvt_pk_bf16_f32 v226, v68, v69
	v_cvt_pk_bf16_f32 v227, v70, v71
	v_cvt_pk_bf16_f32 v228, v64, v65
	v_cvt_pk_bf16_f32 v229, v66, v67
	v_add_u32_e32 v234, 0x42000, v230
	global_store_dwordx4 v234, v[226:229], s[96:97] nt
	v_mul_f32_e32 v60, v60, v76
	v_mul_f32_e32 v61, v61, v76
	v_mul_f32_e32 v62, v62, v76
	v_mul_f32_e32 v63, v63, v76
	v_mul_f32_e32 v52, v52, v76
	v_mul_f32_e32 v53, v53, v76
	v_mul_f32_e32 v54, v54, v76
	v_mul_f32_e32 v55, v55, v76
	v_fma_f32 v210, v60, v136, v174
	v_fma_f32 v211, v61, v137, v175
	v_fma_f32 v212, v62, v138, v176
	v_fma_f32 v213, v63, v139, v177
	v_fma_f32 v214, v52, v140, v178
	v_fma_f32 v215, v53, v141, v179
	v_fma_f32 v216, v54, v142, v180
	v_fma_f32 v217, v55, v143, v181
	v_mul_f32_e32 v218, v56, v76
	v_mul_f32_e32 v219, v57, v76
	v_mul_f32_e32 v220, v58, v76
	v_mul_f32_e32 v221, v59, v76
	v_mul_f32_e32 v222, v48, v76
	v_mul_f32_e32 v223, v49, v76
	v_mul_f32_e32 v224, v50, v76
	v_mul_f32_e32 v225, v51, v76
	v_cvt_pk_bf16_f32 v236, v60, v61
	v_cvt_pk_bf16_f32 v237, v62, v63
	v_cvt_pk_bf16_f32 v238, v52, v53
	v_cvt_pk_bf16_f32 v239, v54, v55
	v_cvt_pk_bf16_f32 v240, v218, v219
	v_cvt_pk_bf16_f32 v241, v220, v221
	v_cvt_pk_bf16_f32 v242, v222, v223
	v_cvt_pk_bf16_f32 v243, v224, v225
	v_add_u32_e32 v234, 0x13400, v233
	v_add_u32_e32 v235, 0x16000, v233
	s_andn2_b64 exec, exec, s[8:9]
	global_store_dwordx4 v234, v[236:239], s[42:43]
	global_store_dwordx4 v235, v[240:243], s[42:43]
	s_mov_b64 exec, s[24:25]
	v_fmac_f32_dpp v210, v60, v128 row_shr:1 row_mask:0xf bank_mask:0xf
	v_fmac_f32_dpp v211, v61, v129 row_shr:1 row_mask:0xf bank_mask:0xf
	v_fmac_f32_dpp v212, v62, v130 row_shr:1 row_mask:0xf bank_mask:0xf
	v_fmac_f32_dpp v213, v63, v131 row_shr:1 row_mask:0xf bank_mask:0xf
	v_fmac_f32_dpp v214, v52, v132 row_shr:1 row_mask:0xf bank_mask:0xf
	v_fmac_f32_dpp v215, v53, v133 row_shr:1 row_mask:0xf bank_mask:0xf
	v_fmac_f32_dpp v216, v54, v134 row_shr:1 row_mask:0xf bank_mask:0xf
	v_fmac_f32_dpp v217, v55, v135 row_shr:1 row_mask:0xf bank_mask:0xf
	v_fmac_f32_dpp v210, v60, v88 row_shr:2 row_mask:0xf bank_mask:0xf
	v_fmac_f32_dpp v211, v61, v89 row_shr:2 row_mask:0xf bank_mask:0xf
	v_fmac_f32_dpp v212, v62, v90 row_shr:2 row_mask:0xf bank_mask:0xf
	v_fmac_f32_dpp v213, v63, v91 row_shr:2 row_mask:0xf bank_mask:0xf
	v_fmac_f32_dpp v214, v52, v92 row_shr:2 row_mask:0xf bank_mask:0xf
	v_fmac_f32_dpp v215, v53, v93 row_shr:2 row_mask:0xf bank_mask:0xf
	v_fmac_f32_dpp v216, v54, v94 row_shr:2 row_mask:0xf bank_mask:0xf
	v_fmac_f32_dpp v217, v55, v95 row_shr:2 row_mask:0xf bank_mask:0xf
	v_exp_f32_e32 v218, v210
	v_exp_f32_e32 v219, v211
	v_exp_f32_e32 v220, v212
	v_exp_f32_e32 v221, v213
	v_exp_f32_e32 v222, v214
	v_exp_f32_e32 v223, v215
	v_exp_f32_e32 v224, v216
	v_exp_f32_e32 v225, v217
;     __device__ __forceinline__ void operator()(const Acc& acc, const Unit& u, int wr, int wc, int fr, int fq, LAS unsigned char* lds, f32x4 epar) const {
;     ...
;                 const float rs = __builtin_amdgcn_rsqf(sq[ai][m] * (1.0f / DM) + RMS_EPS);
;                 float X[NV], Y[NV], o[NV];
;                 if (MODE == 0) {
; #pragma unroll
;                     for (int n = 0; n < 2; ++n)
; #pragma unroll
;                         for (int j = 0; j < 4; ++j) { X[n * 4 + j] = acc[ai][0][m][n][j] * rs; Y[n * 4 + j] = acc[ai][1][m][n][j] * rs; }
;                 } else {
; #pragma unroll
;                     for (int j = 0; j < 4; ++j) { X[j] = (acc[ai][0][m][1][j] * rs) * (acc[ai][1][m][0][j] * rs); Y[j] = acc[ai][0][m][0][j] * rs; }
;                 }
; #pragma unroll
;                 for (int i = 0; i < NV; ++i) {
;                     const float a1 = dpp_rot<0x121>(X[i]), a2 = dpp_rot<0x122>(X[i]);
;                     const float q1 = fr >= 1 ? a1 : p1prev[i], q2 = fr >= 2 ? a2 : p2prev[i];
;                     p1prev[i] = a1; p2prev[i] = a2;
;                     const float cv = w2[i] * X[i] + w1[i] * q1 + w0[i] * q2 + bb[i];
;                     o[i] = MODE == 0 ? silu_f(cv) * Y[i] : cv * Y[i];
;                 }
;                 if (m == 0 && fr < 2) {
;                     bf16_t* hx = halo + ((size_t)strip * 6 + 2 + fr) * C + c0; bf16_t* hy = halo + ((size_t)strip * 6 + 4 + fr) * C + c0;
;                     u32x4 px, py; px.x = cvt_pk_bf16(X[0], X[1]); px.y = cvt_pk_bf16(X[2], X[3]); px.z = cvt_pk_bf16(X[4 % NV], X[5 % NV]); px.w = cvt_pk_bf16(X[6 % NV], X[7 % NV]);
;                     py.x = cvt_pk_bf16(Y[0], Y[1]); py.y = cvt_pk_bf16(Y[2], Y[3]); py.z = cvt_pk_bf16(Y[4 % NV], Y[5 % NV]); py.w = cvt_pk_bf16(Y[6 % NV], Y[7 % NV]);
;                     if (MODE == 0) { *(u32x4*)hx = px; *(u32x4*)hy = py; } else { u32x2 a; a.x = px.x; a.y = px.y; *(u32x2*)hx = a; u32x2 b; b.x = py.x; b.y = py.y; *(u32x2*)hy = b; }
;                 } else {
;                     if (MODE == 0) { u32x4 w; w.x = cvt_pk_bf16(o[0], o[1]); w.y = cvt_pk_bf16(o[2], o[3]); w.z = cvt_pk_bf16(o[4 % NV], o[5 % NV]); w.w = cvt_pk_bf16(o[6 % NV], o[7 % NV]);
;                         __builtin_nontemporal_store(w, (u32x4*)(out + (size_t)r * C + c0)); }
	v_fma_f32 v218, v218, v206, v206
	v_fma_f32 v219, v219, v206, v206
	v_fma_f32 v220, v220, v206, v206
	v_fma_f32 v221, v221, v206, v206
	v_fma_f32 v222, v222, v206, v206
	v_fma_f32 v223, v223, v206, v206
	v_fma_f32 v224, v224, v206, v206
	v_fma_f32 v225, v225, v206, v206
	v_rcp_f32_e32 v218, v218
	v_rcp_f32_e32 v219, v219
	v_rcp_f32_e32 v220, v220
	v_rcp_f32_e32 v221, v221
	v_rcp_f32_e32 v222, v222
	v_rcp_f32_e32 v223, v223
	v_rcp_f32_e32 v224, v224
	v_rcp_f32_e32 v225, v225
	v_mul_f32_e32 v210, v210, v218
	v_mul_f32_e32 v211, v211, v219
	v_mul_f32_e32 v212, v212, v220
	v_mul_f32_e32 v213, v213, v221
	v_mul_f32_e32 v214, v214, v222
	v_mul_f32_e32 v215, v215, v223
	v_mul_f32_e32 v216, v216, v224
	v_mul_f32_e32 v217, v217, v225
	v_mul_f32_e32 v56, v210, v56
	v_mul_f32_e32 v57, v211, v57
	v_mul_f32_e32 v58, v212, v58
	v_mul_f32_e32 v59, v213, v59
	v_mul_f32_e32 v48, v214, v48
	v_mul_f32_e32 v49, v215, v49
	v_mul_f32_e32 v50, v216, v50
	v_mul_f32_e32 v51, v217, v51
	v_cvt_pk_bf16_f32 v226, v56, v57
	v_cvt_pk_bf16_f32 v227, v58, v59
	v_cvt_pk_bf16_f32 v228, v48, v49
	v_cvt_pk_bf16_f32 v229, v50, v51
	v_add_u32_e32 v234, 0xb0000, v230
	s_and_b64 exec, exec, s[8:9]
	global_store_dwordx4 v234, v[226:229], s[96:97] nt
	s_mov_b64 exec, s[24:25]
	v_mul_f32_e32 v44, v44, v77
	v_mul_f32_e32 v45, v45, v77
	v_mul_f32_e32 v46, v46, v77
	v_mul_f32_e32 v47, v47, v77
	v_mul_f32_e32 v40, v40, v77
	v_mul_f32_e32 v41, v41, v77
	v_mul_f32_e32 v42, v42, v77
	v_mul_f32_e32 v43, v43, v77
	v_fma_f32 v210, v44, v136, v174
	v_fma_f32 v211, v45, v137, v175
	v_fma_f32 v212, v46, v138, v176
	v_fma_f32 v213, v47, v139, v177
	v_fma_f32 v214, v40, v140, v178
	v_fma_f32 v215, v41, v141, v179
	v_fma_f32 v216, v42, v142, v180
	v_fma_f32 v217, v43, v143, v181
	v_fmac_f32_dpp v210, v44, v128 row_shr:1 row_mask:0xf bank_mask:0xf
	v_fmac_f32_dpp v211, v45, v129 row_shr:1 row_mask:0xf bank_mask:0xf
	v_fmac_f32_dpp v212, v46, v130 row_shr:1 row_mask:0xf bank_mask:0xf
	v_fmac_f32_dpp v213, v47, v131 row_shr:1 row_mask:0xf bank_mask:0xf
	v_fmac_f32_dpp v214, v40, v132 row_shr:1 row_mask:0xf bank_mask:0xf
	v_fmac_f32_dpp v215, v41, v133 row_shr:1 row_mask:0xf bank_mask:0xf
	v_fmac_f32_dpp v216, v42, v134 row_shr:1 row_mask:0xf bank_mask:0xf
	v_fmac_f32_dpp v217, v43, v135 row_shr:1 row_mask:0xf bank_mask:0xf
	v_fmac_f32_dpp v210, v44, v88 row_shr:2 row_mask:0xf bank_mask:0xf
	v_fmac_f32_dpp v211, v45, v89 row_shr:2 row_mask:0xf bank_mask:0xf
	v_fmac_f32_dpp v212, v46, v90 row_shr:2 row_mask:0xf bank_mask:0xf
	v_fmac_f32_dpp v213, v47, v91 row_shr:2 row_mask:0xf bank_mask:0xf
	v_fmac_f32_dpp v214, v40, v92 row_shr:2 row_mask:0xf bank_mask:0xf
	v_fmac_f32_dpp v215, v41, v93 row_shr:2 row_mask:0xf bank_mask:0xf
	v_fmac_f32_dpp v216, v42, v94 row_shr:2 row_mask:0xf bank_mask:0xf
	v_fmac_f32_dpp v217, v43, v95 row_shr:2 row_mask:0xf bank_mask:0xf
	v_fmac_f32_dpp v210, v60, v128 row_shl:15 row_mask:0xf bank_mask:0xf
	v_fmac_f32_dpp v211, v61, v129 row_shl:15 row_mask:0xf bank_mask:0xf
	v_fmac_f32_dpp v212, v62, v130 row_shl:15 row_mask:0xf bank_mask:0xf
	v_fmac_f32_dpp v213, v63, v131 row_shl:15 row_mask:0xf bank_mask:0xf
	v_fmac_f32_dpp v214, v52, v132 row_shl:15 row_mask:0xf bank_mask:0xf
	v_fmac_f32_dpp v215, v53, v133 row_shl:15 row_mask:0xf bank_mask:0xf
	v_fmac_f32_dpp v216, v54, v134 row_shl:15 row_mask:0xf bank_mask:0xf
	v_fmac_f32_dpp v217, v55, v135 row_shl:15 row_mask:0xf bank_mask:0xf
	v_fmac_f32_dpp v210, v60, v88 row_shl:14 row_mask:0xf bank_mask:0xf
	v_fmac_f32_dpp v211, v61, v89 row_shl:14 row_mask:0xf bank_mask:0xf
	v_fmac_f32_dpp v212, v62, v90 row_shl:14 row_mask:0xf bank_mask:0xf
	v_fmac_f32_dpp v213, v63, v91 row_shl:14 row_mask:0xf bank_mask:0xf
	v_fmac_f32_dpp v214, v52, v92 row_shl:14 row_mask:0xf bank_mask:0xf
	v_fmac_f32_dpp v215, v53, v93 row_shl:14 row_mask:0xf bank_mask:0xf
	v_fmac_f32_dpp v216, v54, v94 row_shl:14 row_mask:0xf bank_mask:0xf
	v_fmac_f32_dpp v217, v55, v95 row_shl:14 row_mask:0xf bank_mask:0xf
	v_exp_f32_e32 v218, v210
	v_exp_f32_e32 v219, v211
	v_exp_f32_e32 v220, v212
	v_exp_f32_e32 v221, v213
	v_exp_f32_e32 v222, v214
	v_exp_f32_e32 v223, v215
	v_exp_f32_e32 v224, v216
	v_exp_f32_e32 v225, v217
	v_fma_f32 v218, v218, v207, v207
	v_fma_f32 v219, v219, v207, v207
	v_fma_f32 v220, v220, v207, v207
	v_fma_f32 v221, v221, v207, v207
	v_fma_f32 v222, v222, v207, v207
	v_fma_f32 v223, v223, v207, v207
	v_fma_f32 v224, v224, v207, v207
	v_fma_f32 v225, v225, v207, v207
	v_rcp_f32_e32 v218, v218
	v_rcp_f32_e32 v219, v219
	v_rcp_f32_e32 v220, v220
	v_rcp_f32_e32 v221, v221
	v_rcp_f32_e32 v222, v222
	v_rcp_f32_e32 v223, v223
	v_rcp_f32_e32 v224, v224
	v_rcp_f32_e32 v225, v225
	v_mul_f32_e32 v210, v210, v218
	v_mul_f32_e32 v211, v211, v219
	v_mul_f32_e32 v212, v212, v220
	v_mul_f32_e32 v213, v213, v221
	v_mul_f32_e32 v214, v214, v222
	v_mul_f32_e32 v215, v215, v223
	v_mul_f32_e32 v216, v216, v224
	v_mul_f32_e32 v217, v217, v225
	v_mul_f32_e32 v36, v210, v36
	v_mul_f32_e32 v37, v211, v37
	v_mul_f32_e32 v38, v212, v38
	v_mul_f32_e32 v39, v213, v39
	v_mul_f32_e32 v32, v214, v32
	v_mul_f32_e32 v33, v215, v33
	v_mul_f32_e32 v34, v216, v34
	v_mul_f32_e32 v35, v217, v35
	v_cvt_pk_bf16_f32 v226, v36, v37
	v_cvt_pk_bf16_f32 v227, v38, v39
	v_cvt_pk_bf16_f32 v228, v32, v33
	v_cvt_pk_bf16_f32 v229, v34, v35
	v_add_u32_e32 v234, 0xc6000, v230
	global_store_dwordx4 v234, v[226:229], s[96:97] nt
	v_mul_f32_e32 v28, v28, v78
	v_mul_f32_e32 v29, v29, v78
	v_mul_f32_e32 v30, v30, v78
	v_mul_f32_e32 v31, v31, v78
	v_mul_f32_e32 v24, v24, v78
	v_mul_f32_e32 v25, v25, v78
	v_mul_f32_e32 v26, v26, v78
	v_mul_f32_e32 v27, v27, v78
	v_fma_f32 v210, v28, v136, v174
;     __device__ __forceinline__ void operator()(const Acc& acc, const Unit& u, int wr, int wc, int fr, int fq, LAS unsigned char* lds, f32x4 epar) const {
;     ...
;                 const float rs = __builtin_amdgcn_rsqf(sq[ai][m] * (1.0f / DM) + RMS_EPS);
;                 float X[NV], Y[NV], o[NV];
;                 if (MODE == 0) {
; #pragma unroll
;                     for (int n = 0; n < 2; ++n)
; #pragma unroll
;                         for (int j = 0; j < 4; ++j) { X[n * 4 + j] = acc[ai][0][m][n][j] * rs; Y[n * 4 + j] = acc[ai][1][m][n][j] * rs; }
;                 } else {
; #pragma unroll
;                     for (int j = 0; j < 4; ++j) { X[j] = (acc[ai][0][m][1][j] * rs) * (acc[ai][1][m][0][j] * rs); Y[j] = acc[ai][0][m][0][j] * rs; }
;                 }
; #pragma unroll
;                 for (int i = 0; i < NV; ++i) {
;                     const float a1 = dpp_rot<0x121>(X[i]), a2 = dpp_rot<0x122>(X[i]);
;                     const float q1 = fr >= 1 ? a1 : p1prev[i], q2 = fr >= 2 ? a2 : p2prev[i];
;                     p1prev[i] = a1; p2prev[i] = a2;
;                     const float cv = w2[i] * X[i] + w1[i] * q1 + w0[i] * q2 + bb[i];
;                     o[i] = MODE == 0 ? silu_f(cv) * Y[i] : cv * Y[i];
;                 }
;                 if (m == 0 && fr < 2) {
;                     bf16_t* hx = halo + ((size_t)strip * 6 + 2 + fr) * C + c0; bf16_t* hy = halo + ((size_t)strip * 6 + 4 + fr) * C + c0;
;                     u32x4 px, py; px.x = cvt_pk_bf16(X[0], X[1]); px.y = cvt_pk_bf16(X[2], X[3]); px.z = cvt_pk_bf16(X[4 % NV], X[5 % NV]); px.w = cvt_pk_bf16(X[6 % NV], X[7 % NV]);
;                     py.x = cvt_pk_bf16(Y[0], Y[1]); py.y = cvt_pk_bf16(Y[2], Y[3]); py.z = cvt_pk_bf16(Y[4 % NV], Y[5 % NV]); py.w = cvt_pk_bf16(Y[6 % NV], Y[7 % NV]);
;                     if (MODE == 0) { *(u32x4*)hx = px; *(u32x4*)hy = py; } else { u32x2 a; a.x = px.x; a.y = px.y; *(u32x2*)hx = a; u32x2 b; b.x = py.x; b.y = py.y; *(u32x2*)hy = b; }
;                 } else {
;                     if (MODE == 0) { u32x4 w; w.x = cvt_pk_bf16(o[0], o[1]); w.y = cvt_pk_bf16(o[2], o[3]); w.z = cvt_pk_bf16(o[4 % NV], o[5 % NV]); w.w = cvt_pk_bf16(o[6 % NV], o[7 % NV]);
;                         __builtin_nontemporal_store(w, (u32x4*)(out + (size_t)r * C + c0)); }
	v_fma_f32 v211, v29, v137, v175
	v_fma_f32 v212, v30, v138, v176
	v_fma_f32 v213, v31, v139, v177
	v_fma_f32 v214, v24, v140, v178
	v_fma_f32 v215, v25, v141, v179
	v_fma_f32 v216, v26, v142, v180
	v_fma_f32 v217, v27, v143, v181
	v_fmac_f32_dpp v210, v28, v128 row_shr:1 row_mask:0xf bank_mask:0xf
	v_fmac_f32_dpp v211, v29, v129 row_shr:1 row_mask:0xf bank_mask:0xf
	v_fmac_f32_dpp v212, v30, v130 row_shr:1 row_mask:0xf bank_mask:0xf
	v_fmac_f32_dpp v213, v31, v131 row_shr:1 row_mask:0xf bank_mask:0xf
	v_fmac_f32_dpp v214, v24, v132 row_shr:1 row_mask:0xf bank_mask:0xf
	v_fmac_f32_dpp v215, v25, v133 row_shr:1 row_mask:0xf bank_mask:0xf
	v_fmac_f32_dpp v216, v26, v134 row_shr:1 row_mask:0xf bank_mask:0xf
	v_fmac_f32_dpp v217, v27, v135 row_shr:1 row_mask:0xf bank_mask:0xf
	v_fmac_f32_dpp v210, v28, v88 row_shr:2 row_mask:0xf bank_mask:0xf
	v_fmac_f32_dpp v211, v29, v89 row_shr:2 row_mask:0xf bank_mask:0xf
	v_fmac_f32_dpp v212, v30, v90 row_shr:2 row_mask:0xf bank_mask:0xf
	v_fmac_f32_dpp v213, v31, v91 row_shr:2 row_mask:0xf bank_mask:0xf
	v_fmac_f32_dpp v214, v24, v92 row_shr:2 row_mask:0xf bank_mask:0xf
	v_fmac_f32_dpp v215, v25, v93 row_shr:2 row_mask:0xf bank_mask:0xf
	v_fmac_f32_dpp v216, v26, v94 row_shr:2 row_mask:0xf bank_mask:0xf
	v_fmac_f32_dpp v217, v27, v95 row_shr:2 row_mask:0xf bank_mask:0xf
	v_fmac_f32_dpp v210, v44, v128 row_shl:15 row_mask:0xf bank_mask:0xf
	v_fmac_f32_dpp v211, v45, v129 row_shl:15 row_mask:0xf bank_mask:0xf
	v_fmac_f32_dpp v212, v46, v130 row_shl:15 row_mask:0xf bank_mask:0xf
	v_fmac_f32_dpp v213, v47, v131 row_shl:15 row_mask:0xf bank_mask:0xf
	v_fmac_f32_dpp v214, v40, v132 row_shl:15 row_mask:0xf bank_mask:0xf
	v_fmac_f32_dpp v215, v41, v133 row_shl:15 row_mask:0xf bank_mask:0xf
	v_fmac_f32_dpp v216, v42, v134 row_shl:15 row_mask:0xf bank_mask:0xf
	v_fmac_f32_dpp v217, v43, v135 row_shl:15 row_mask:0xf bank_mask:0xf
	v_fmac_f32_dpp v210, v44, v88 row_shl:14 row_mask:0xf bank_mask:0xf
	v_fmac_f32_dpp v211, v45, v89 row_shl:14 row_mask:0xf bank_mask:0xf
	v_fmac_f32_dpp v212, v46, v90 row_shl:14 row_mask:0xf bank_mask:0xf
	v_fmac_f32_dpp v213, v47, v91 row_shl:14 row_mask:0xf bank_mask:0xf
	v_fmac_f32_dpp v214, v40, v92 row_shl:14 row_mask:0xf bank_mask:0xf
	v_fmac_f32_dpp v215, v41, v93 row_shl:14 row_mask:0xf bank_mask:0xf
	v_fmac_f32_dpp v216, v42, v94 row_shl:14 row_mask:0xf bank_mask:0xf
	v_fmac_f32_dpp v217, v43, v95 row_shl:14 row_mask:0xf bank_mask:0xf
	v_exp_f32_e32 v218, v210
	v_exp_f32_e32 v219, v211
	v_exp_f32_e32 v220, v212
	v_exp_f32_e32 v221, v213
	v_exp_f32_e32 v222, v214
	v_exp_f32_e32 v223, v215
	v_exp_f32_e32 v224, v216
	v_exp_f32_e32 v225, v217
	v_fma_f32 v218, v218, v208, v208
	v_fma_f32 v219, v219, v208, v208
	v_fma_f32 v220, v220, v208, v208
	v_fma_f32 v221, v221, v208, v208
	v_fma_f32 v222, v222, v208, v208
	v_fma_f32 v223, v223, v208, v208
	v_fma_f32 v224, v224, v208, v208
	v_fma_f32 v225, v225, v208, v208
	v_rcp_f32_e32 v218, v218
	v_rcp_f32_e32 v219, v219
	v_rcp_f32_e32 v220, v220
	v_rcp_f32_e32 v221, v221
	v_rcp_f32_e32 v222, v222
	v_rcp_f32_e32 v223, v223
	v_rcp_f32_e32 v224, v224
	v_rcp_f32_e32 v225, v225
	v_mul_f32_e32 v210, v210, v218
	v_mul_f32_e32 v211, v211, v219
	v_mul_f32_e32 v212, v212, v220
	v_mul_f32_e32 v213, v213, v221
	v_mul_f32_e32 v214, v214, v222
	v_mul_f32_e32 v215, v215, v223
	v_mul_f32_e32 v216, v216, v224
	v_mul_f32_e32 v217, v217, v225
	v_mul_f32_e32 v20, v210, v20
	v_mul_f32_e32 v21, v211, v21
	v_mul_f32_e32 v22, v212, v22
	v_mul_f32_e32 v23, v213, v23
	v_mul_f32_e32 v16, v214, v16
	v_mul_f32_e32 v17, v215, v17
	v_mul_f32_e32 v18, v216, v18
	v_mul_f32_e32 v19, v217, v19
	v_cvt_pk_bf16_f32 v226, v20, v21
	v_cvt_pk_bf16_f32 v227, v22, v23
	v_cvt_pk_bf16_f32 v228, v16, v17
	v_cvt_pk_bf16_f32 v229, v18, v19
	v_add_u32_e32 v234, 0xdc000, v230
	global_store_dwordx4 v234, v[226:229], s[96:97] nt
	v_mul_f32_e32 v12, v12, v79
	v_mul_f32_e32 v13, v13, v79
	v_mul_f32_e32 v14, v14, v79
	v_mul_f32_e32 v15, v15, v79
	v_mul_f32_e32 v8, v8, v79
	v_mul_f32_e32 v9, v9, v79
	v_mul_f32_e32 v10, v10, v79
	v_mul_f32_e32 v11, v11, v79
	v_fma_f32 v210, v12, v136, v174
; __device__ __forceinline__ float silu_f(float x) { return x * __builtin_amdgcn_rcpf(1.0f + __builtin_amdgcn_exp2f(x * -1.44269504f)); }
;     __device__ __forceinline__ void operator()(const Acc& acc, const Unit& u, int wr, int wc, int fr, int fq, LAS unsigned char* lds, f32x4 epar) const {
;     ...
;                 for (int i = 0; i < NV; ++i) {
;                     const float a1 = dpp_rot<0x121>(X[i]), a2 = dpp_rot<0x122>(X[i]);
;                     const float q1 = fr >= 1 ? a1 : p1prev[i], q2 = fr >= 2 ? a2 : p2prev[i];
;                     p1prev[i] = a1; p2prev[i] = a2;
;                     const float cv = w2[i] * X[i] + w1[i] * q1 + w0[i] * q2 + bb[i];
;                     o[i] = MODE == 0 ? silu_f(cv) * Y[i] : cv * Y[i];
;                 }
;                 if (m == 0 && fr < 2) {
;                     bf16_t* hx = halo + ((size_t)strip * 6 + 2 + fr) * C + c0; bf16_t* hy = halo + ((size_t)strip * 6 + 4 + fr) * C + c0;
;                     u32x4 px, py; px.x = cvt_pk_bf16(X[0], X[1]); px.y = cvt_pk_bf16(X[2], X[3]); px.z = cvt_pk_bf16(X[4 % NV], X[5 % NV]); px.w = cvt_pk_bf16(X[6 % NV], X[7 % NV]);
;                     py.x = cvt_pk_bf16(Y[0], Y[1]); py.y = cvt_pk_bf16(Y[2], Y[3]); py.z = cvt_pk_bf16(Y[4 % NV], Y[5 % NV]); py.w = cvt_pk_bf16(Y[6 % NV], Y[7 % NV]);
;                     if (MODE == 0) { *(u32x4*)hx = px; *(u32x4*)hy = py; } else { u32x2 a; a.x = px.x; a.y = px.y; *(u32x2*)hx = a; u32x2 b; b.x = py.x; b.y = py.y; *(u32x2*)hy = b; }
;                 } else {
;                     if (MODE == 0) { u32x4 w; w.x = cvt_pk_bf16(o[0], o[1]); w.y = cvt_pk_bf16(o[2], o[3]); w.z = cvt_pk_bf16(o[4 % NV], o[5 % NV]); w.w = cvt_pk_bf16(o[6 % NV], o[7 % NV]);
;                         __builtin_nontemporal_store(w, (u32x4*)(out + (size_t)r * C + c0)); }
;                     else { u32x2 w; w.x = cvt_pk_bf16(o[0], o[1]); w.y = cvt_pk_bf16(o[2], o[3]); __builtin_nontemporal_store(w, (u32x2*)(out + (size_t)r * C + c0)); }
;                 }
;                 if (m == 3 && fr >= 14) { bf16_t* hx = halo + ((size_t)strip * 6 + (fr - 14)) * C + c0;
;                     u32x4 px; px.x = cvt_pk_bf16(X[0], X[1]); px.y = cvt_pk_bf16(X[2], X[3]); px.z = cvt_pk_bf16(X[4 % NV], X[5 % NV]); px.w = cvt_pk_bf16(X[6 % NV], X[7 % NV]);
;                     if (MODE == 0) *(u32x4*)hx = px; else { u32x2 a; a.x = px.x; a.y = px.y; *(u32x2*)hx = a; } }
	v_fma_f32 v211, v13, v137, v175
	v_fma_f32 v212, v14, v138, v176
	v_fma_f32 v213, v15, v139, v177
	v_fma_f32 v214, v8, v140, v178
	v_fma_f32 v215, v9, v141, v179
	v_fma_f32 v216, v10, v142, v180
	v_fma_f32 v217, v11, v143, v181
	v_cvt_pk_bf16_f32 v236, v12, v13
	v_cvt_pk_bf16_f32 v237, v14, v15
	v_cvt_pk_bf16_f32 v238, v8, v9
	v_cvt_pk_bf16_f32 v239, v10, v11
	v_add_u32_e32 v235, 0xffffd400, v233
	s_and_b64 exec, exec, s[10:11]
	global_store_dwordx4 v235, v[236:239], s[42:43]
	s_mov_b64 exec, s[24:25]
	v_fmac_f32_dpp v210, v12, v128 row_shr:1 row_mask:0xf bank_mask:0xf
	v_fmac_f32_dpp v211, v13, v129 row_shr:1 row_mask:0xf bank_mask:0xf
	v_fmac_f32_dpp v212, v14, v130 row_shr:1 row_mask:0xf bank_mask:0xf
	v_fmac_f32_dpp v213, v15, v131 row_shr:1 row_mask:0xf bank_mask:0xf
	v_fmac_f32_dpp v214, v8, v132 row_shr:1 row_mask:0xf bank_mask:0xf
	v_fmac_f32_dpp v215, v9, v133 row_shr:1 row_mask:0xf bank_mask:0xf
	v_fmac_f32_dpp v216, v10, v134 row_shr:1 row_mask:0xf bank_mask:0xf
	v_fmac_f32_dpp v217, v11, v135 row_shr:1 row_mask:0xf bank_mask:0xf
	v_fmac_f32_dpp v210, v12, v88 row_shr:2 row_mask:0xf bank_mask:0xf
	v_fmac_f32_dpp v211, v13, v89 row_shr:2 row_mask:0xf bank_mask:0xf
	v_fmac_f32_dpp v212, v14, v90 row_shr:2 row_mask:0xf bank_mask:0xf
	v_fmac_f32_dpp v213, v15, v91 row_shr:2 row_mask:0xf bank_mask:0xf
	v_fmac_f32_dpp v214, v8, v92 row_shr:2 row_mask:0xf bank_mask:0xf
	v_fmac_f32_dpp v215, v9, v93 row_shr:2 row_mask:0xf bank_mask:0xf
	v_fmac_f32_dpp v216, v10, v94 row_shr:2 row_mask:0xf bank_mask:0xf
	v_fmac_f32_dpp v217, v11, v95 row_shr:2 row_mask:0xf bank_mask:0xf
	v_fmac_f32_dpp v210, v28, v128 row_shl:15 row_mask:0xf bank_mask:0xf
	v_fmac_f32_dpp v211, v29, v129 row_shl:15 row_mask:0xf bank_mask:0xf
	v_fmac_f32_dpp v212, v30, v130 row_shl:15 row_mask:0xf bank_mask:0xf
	v_fmac_f32_dpp v213, v31, v131 row_shl:15 row_mask:0xf bank_mask:0xf
	v_fmac_f32_dpp v214, v24, v132 row_shl:15 row_mask:0xf bank_mask:0xf
	v_fmac_f32_dpp v215, v25, v133 row_shl:15 row_mask:0xf bank_mask:0xf
	v_fmac_f32_dpp v216, v26, v134 row_shl:15 row_mask:0xf bank_mask:0xf
	v_fmac_f32_dpp v217, v27, v135 row_shl:15 row_mask:0xf bank_mask:0xf
	v_fmac_f32_dpp v210, v28, v88 row_shl:14 row_mask:0xf bank_mask:0xf
	v_fmac_f32_dpp v211, v29, v89 row_shl:14 row_mask:0xf bank_mask:0xf
	v_fmac_f32_dpp v212, v30, v90 row_shl:14 row_mask:0xf bank_mask:0xf
	v_fmac_f32_dpp v213, v31, v91 row_shl:14 row_mask:0xf bank_mask:0xf
	v_fmac_f32_dpp v214, v24, v92 row_shl:14 row_mask:0xf bank_mask:0xf
	v_fmac_f32_dpp v215, v25, v93 row_shl:14 row_mask:0xf bank_mask:0xf
	v_fmac_f32_dpp v216, v26, v94 row_shl:14 row_mask:0xf bank_mask:0xf
	v_fmac_f32_dpp v217, v27, v95 row_shl:14 row_mask:0xf bank_mask:0xf
	v_exp_f32_e32 v218, v210
	v_exp_f32_e32 v219, v211
	v_exp_f32_e32 v220, v212
	v_exp_f32_e32 v221, v213
	v_exp_f32_e32 v222, v214
	v_exp_f32_e32 v223, v215
	v_exp_f32_e32 v224, v216
	v_exp_f32_e32 v225, v217
	v_fma_f32 v218, v218, v209, v209
	v_fma_f32 v219, v219, v209, v209
	v_fma_f32 v220, v220, v209, v209
	v_fma_f32 v221, v221, v209, v209
	v_fma_f32 v222, v222, v209, v209
	v_fma_f32 v223, v223, v209, v209
	v_fma_f32 v224, v224, v209, v209
	v_fma_f32 v225, v225, v209, v209
	v_rcp_f32_e32 v218, v218
	v_rcp_f32_e32 v219, v219
	v_rcp_f32_e32 v220, v220
	v_rcp_f32_e32 v221, v221
	v_rcp_f32_e32 v222, v222
	v_rcp_f32_e32 v223, v223
	v_rcp_f32_e32 v224, v224
	v_rcp_f32_e32 v225, v225
	v_mul_f32_e32 v210, v210, v218
	v_mul_f32_e32 v211, v211, v219
	v_mul_f32_e32 v212, v212, v220
	v_mul_f32_e32 v213, v213, v221
	v_mul_f32_e32 v214, v214, v222
	v_mul_f32_e32 v215, v215, v223
	v_mul_f32_e32 v216, v216, v224
	v_mul_f32_e32 v217, v217, v225
	v_mul_f32_e32 v4, v210, v4
	v_mul_f32_e32 v5, v211, v5
	v_mul_f32_e32 v6, v212, v6
	v_mul_f32_e32 v7, v213, v7
	v_mul_f32_e32 v0, v214, v0
	v_mul_f32_e32 v1, v215, v1
	v_mul_f32_e32 v2, v216, v2
	v_mul_f32_e32 v3, v217, v3
	v_cvt_pk_bf16_f32 v226, v4, v5
	v_cvt_pk_bf16_f32 v227, v6, v7
	v_cvt_pk_bf16_f32 v228, v0, v1
	v_cvt_pk_bf16_f32 v229, v2, v3
	v_add_u32_e32 v234, 0xf2000, v230
	global_store_dwordx4 v234, v[226:229], s[96:97] nt
